# load_q: prefetch all rope cos/sin table groups up front (DSA, dilated A/B, MLA) instead of serialized load-wait groups
# speedup vs baseline: 1.0056x; 1.0036x over previous
.LBB0_996:
	s_xor_b64 s[16:17], s[0:1], -1
	s_and_b64 s[0:1], s[0:1], exec
	s_cselect_b32 s0, s36, s35
	s_lshl_b32 s7, s0, 8
	s_or_b32 s2, s7, s6
	v_add_u32_e32 v2, s2, v175
	s_movk_i32 s1, 0x1800
	v_mad_i64_i32 v[46:47], s[4:5], v2, s1, v[168:169]
	global_load_dwordx4 v[18:21], v[46:47], off
	global_load_dwordx4 v[22:25], v[46:47], off offset:32
	global_load_dwordx4 v[26:29], v[46:47], off offset:64
	global_load_dwordx4 v[30:33], v[46:47], off offset:96
	v_ashrrev_i32_e32 v3, 31, v2
	v_lshlrev_b64 v[50:51], 8, v[2:3]
	global_load_dwordx4 v[10:13], v[46:47], off offset:256
	global_load_dwordx4 v[2:5], v[46:47], off offset:288
	global_load_dwordx4 v[14:17], v[46:47], off offset:320
	global_load_dwordx4 v[6:9], v[46:47], off offset:352
	global_load_dwordx4 v[34:37], v[46:47], off offset:128
	global_load_dwordx4 v[38:41], v[46:47], off offset:160
	global_load_dwordx4 v[42:45], v[46:47], off offset:192
	s_nop 0
	global_load_dwordx4 v[46:49], v[46:47], off offset:224
	s_lshl_b32 s38, s0, 2
	v_mov_b32_e32 v171, v1
	s_mov_b64 s[20:21], 0x100
	s_add_i32 s38, s38, 4
	v_add_u32_e32 v181, s7, v174
	s_mov_b32 s42, 2
	v_or_b32_e32 v182, 31, v181
	s_mov_b32 s43, 0
	v_mov_b32_e32 v180, 0
	v_mov_b32_e32 v186, 0xf149f2ca
	s_movk_i32 s44, 0xff00
	s_mov_b32 s45, 0
	s_mov_b32 s37, 0
	s_waitcnt vmcnt(11)
	v_lshlrev_b32_e32 v0, 16, v18
	v_and_b32_e32 v18, 0xffff0000, v18
	v_lshlrev_b32_e32 v52, 16, v19
	v_and_b32_e32 v19, 0xffff0000, v19
	v_lshlrev_b32_e32 v53, 16, v20
	v_and_b32_e32 v20, 0xffff0000, v20
	v_mul_f32_e32 v18, 0x3dd53b94, v18
	v_mul_f32_e32 v19, 0x3dd53b94, v19
	v_mul_f32_e32 v20, 0x3dd53b94, v20
	v_lshlrev_b32_e32 v54, 16, v21
	v_and_b32_e32 v21, 0xffff0000, v21
	s_waitcnt vmcnt(10)
	v_lshlrev_b32_e32 v55, 16, v22
	v_and_b32_e32 v22, 0xffff0000, v22
	v_lshlrev_b32_e32 v56, 16, v23
	v_and_b32_e32 v23, 0xffff0000, v23
	v_lshlrev_b32_e32 v57, 16, v24
	v_and_b32_e32 v24, 0xffff0000, v24
	v_mul_f32_e32 v0, 0x3dd53b94, v0
	v_mul_f32_e32 v52, 0x3dd53b94, v52
	v_mul_f32_e32 v53, 0x3dd53b94, v53
	v_cvt_pk_bf16_f32 v112, v0, v18
	v_cvt_pk_bf16_f32 v113, v52, v19
	v_cvt_pk_bf16_f32 v114, v53, v20
	s_waitcnt vmcnt(8)
	v_and_b32_e32 v18, 0xffff0000, v32
	v_lshlrev_b32_e32 v19, 16, v33
	v_and_b32_e32 v20, 0xffff0000, v33
	v_lshlrev_b32_e32 v58, 16, v25
	v_and_b32_e32 v25, 0xffff0000, v25
	v_lshlrev_b32_e32 v59, 16, v26
	v_and_b32_e32 v26, 0xffff0000, v26
	v_lshlrev_b32_e32 v60, 16, v27
	v_and_b32_e32 v27, 0xffff0000, v27
	v_lshlrev_b32_e32 v61, 16, v28
	v_and_b32_e32 v28, 0xffff0000, v28
	v_lshlrev_b32_e32 v62, 16, v29
	v_and_b32_e32 v29, 0xffff0000, v29
	v_lshlrev_b32_e32 v63, 16, v30
	v_and_b32_e32 v30, 0xffff0000, v30
	v_lshlrev_b32_e32 v64, 16, v31
	v_and_b32_e32 v31, 0xffff0000, v31
	v_mul_f32_e32 v21, 0x3dd53b94, v21
	v_mul_f32_e32 v22, 0x3dd53b94, v22
	v_mul_f32_e32 v23, 0x3dd53b94, v23
	v_mul_f32_e32 v24, 0x3dd53b94, v24
	v_lshlrev_b32_e32 v0, 16, v32
	v_mul_f32_e32 v18, 0x3dd53b94, v18
	v_mul_f32_e32 v19, 0x3dd53b94, v19
	v_mul_f32_e32 v20, 0x3dd53b94, v20
	v_mul_f32_e32 v54, 0x3dd53b94, v54
	v_mul_f32_e32 v55, 0x3dd53b94, v55
	v_mul_f32_e32 v56, 0x3dd53b94, v56
	v_mul_f32_e32 v57, 0x3dd53b94, v57
	v_mul_f32_e32 v58, 0x3dd53b94, v58
	v_mul_f32_e32 v25, 0x3dd53b94, v25
	v_mul_f32_e32 v59, 0x3dd53b94, v59
	v_mul_f32_e32 v26, 0x3dd53b94, v26
	v_mul_f32_e32 v60, 0x3dd53b94, v60
	v_mul_f32_e32 v27, 0x3dd53b94, v27
	v_mul_f32_e32 v61, 0x3dd53b94, v61
	v_mul_f32_e32 v28, 0x3dd53b94, v28
	v_mul_f32_e32 v62, 0x3dd53b94, v62
	v_mul_f32_e32 v29, 0x3dd53b94, v29
	v_mul_f32_e32 v63, 0x3dd53b94, v63
	v_mul_f32_e32 v30, 0x3dd53b94, v30
	v_mul_f32_e32 v64, 0x3dd53b94, v64
	v_mul_f32_e32 v31, 0x3dd53b94, v31
	v_cvt_pk_bf16_f32 v115, v54, v21
	v_cvt_pk_bf16_f32 v116, v55, v22
	v_cvt_pk_bf16_f32 v117, v56, v23
	v_cvt_pk_bf16_f32 v118, v57, v24
	v_cvt_pk_bf16_f32 v119, v58, v25
	v_cvt_pk_bf16_f32 v120, v59, v26
	v_cvt_pk_bf16_f32 v121, v60, v27
	v_cvt_pk_bf16_f32 v122, v61, v28
	v_cvt_pk_bf16_f32 v123, v62, v29
	v_mul_f32_e32 v0, 0x3dd53b94, v0
	v_cvt_pk_bf16_f32 v124, v63, v30
	v_cvt_pk_bf16_f32 v125, v64, v31
	v_cvt_pk_bf16_f32 v126, v0, v18
	v_cvt_pk_bf16_f32 v127, v19, v20
	s_waitcnt vmcnt(3)
	v_and_b32_e32 v18, 0xffff0000, v34
	v_lshlrev_b32_e32 v19, 16, v35
	v_and_b32_e32 v20, 0xffff0000, v35
	v_lshlrev_b32_e32 v21, 16, v36
	v_and_b32_e32 v22, 0xffff0000, v36
	v_lshlrev_b32_e32 v23, 16, v37
	v_and_b32_e32 v24, 0xffff0000, v37
	v_lshlrev_b32_e32 v0, 16, v34
	v_mul_f32_e32 v18, 0x3dd53b94, v18
	v_mul_f32_e32 v19, 0x3dd53b94, v19
	v_mul_f32_e32 v20, 0x3dd53b94, v20
	v_mul_f32_e32 v21, 0x3dd53b94, v21
	v_mul_f32_e32 v22, 0x3dd53b94, v22
	v_mul_f32_e32 v23, 0x3dd53b94, v23
	v_mul_f32_e32 v24, 0x3dd53b94, v24
	v_mul_f32_e32 v0, 0x3dd53b94, v0
	v_cvt_pk_bf16_f32 v128, v0, v18
	v_cvt_pk_bf16_f32 v129, v19, v20
	v_cvt_pk_bf16_f32 v130, v21, v22
	v_cvt_pk_bf16_f32 v131, v23, v24
	s_waitcnt vmcnt(2)
	v_and_b32_e32 v18, 0xffff0000, v38
	v_lshlrev_b32_e32 v19, 16, v39
	v_and_b32_e32 v20, 0xffff0000, v39
	v_lshlrev_b32_e32 v21, 16, v40
	v_and_b32_e32 v22, 0xffff0000, v40
	v_lshlrev_b32_e32 v23, 16, v41
	v_and_b32_e32 v24, 0xffff0000, v41
	v_lshlrev_b32_e32 v0, 16, v38
	v_mul_f32_e32 v18, 0x3dd53b94, v18
	v_mul_f32_e32 v19, 0x3dd53b94, v19
	v_mul_f32_e32 v20, 0x3dd53b94, v20
	v_mul_f32_e32 v21, 0x3dd53b94, v21
	v_mul_f32_e32 v22, 0x3dd53b94, v22
	v_mul_f32_e32 v23, 0x3dd53b94, v23
	v_mul_f32_e32 v24, 0x3dd53b94, v24
	v_mul_f32_e32 v0, 0x3dd53b94, v0
	v_cvt_pk_bf16_f32 v132, v0, v18
	v_cvt_pk_bf16_f32 v133, v19, v20
	v_cvt_pk_bf16_f32 v134, v21, v22
	v_cvt_pk_bf16_f32 v135, v23, v24
	s_waitcnt vmcnt(1)
	v_and_b32_e32 v18, 0xffff0000, v42
	v_lshlrev_b32_e32 v19, 16, v43
	v_and_b32_e32 v20, 0xffff0000, v43
	v_lshlrev_b32_e32 v21, 16, v44
	v_and_b32_e32 v22, 0xffff0000, v44
	v_lshlrev_b32_e32 v23, 16, v45
	v_and_b32_e32 v24, 0xffff0000, v45
	v_lshlrev_b32_e32 v0, 16, v42
	v_mul_f32_e32 v18, 0x3dd53b94, v18
	v_mul_f32_e32 v19, 0x3dd53b94, v19
	v_mul_f32_e32 v20, 0x3dd53b94, v20
	v_mul_f32_e32 v21, 0x3dd53b94, v21
	v_mul_f32_e32 v22, 0x3dd53b94, v22
	v_mul_f32_e32 v23, 0x3dd53b94, v23
	v_mul_f32_e32 v24, 0x3dd53b94, v24
	v_mul_f32_e32 v0, 0x3dd53b94, v0
	v_cvt_pk_bf16_f32 v136, v0, v18
	v_cvt_pk_bf16_f32 v137, v19, v20
	v_cvt_pk_bf16_f32 v138, v21, v22
	v_cvt_pk_bf16_f32 v139, v23, v24
	s_waitcnt vmcnt(0)
	v_and_b32_e32 v18, 0xffff0000, v46
	v_lshlrev_b32_e32 v19, 16, v47
	v_and_b32_e32 v20, 0xffff0000, v47
	v_lshlrev_b32_e32 v21, 16, v48
	v_and_b32_e32 v22, 0xffff0000, v48
	v_lshlrev_b32_e32 v23, 16, v49
	v_and_b32_e32 v24, 0xffff0000, v49
	v_lshlrev_b32_e32 v0, 16, v46
	v_mul_f32_e32 v18, 0x3dd53b94, v18
	v_mul_f32_e32 v19, 0x3dd53b94, v19
	v_mul_f32_e32 v20, 0x3dd53b94, v20
	v_mul_f32_e32 v21, 0x3dd53b94, v21
	v_mul_f32_e32 v22, 0x3dd53b94, v22
	v_mul_f32_e32 v23, 0x3dd53b94, v23
	v_mul_f32_e32 v24, 0x3dd53b94, v24
	v_lshl_add_u64 v[34:35], v[164:165], 0, v[50:51]
	v_mul_f32_e32 v0, 0x3dd53b94, v0
	v_cvt_pk_bf16_f32 v140, v0, v18
	v_cvt_pk_bf16_f32 v141, v19, v20
	v_cvt_pk_bf16_f32 v142, v21, v22
	v_cvt_pk_bf16_f32 v143, v23, v24
	global_load_dwordx4 v[100:103], v[34:35], off offset:128
	global_load_dwordx4 v[104:107], v[34:35], off offset:144
	global_load_dwordx4 v[108:111], v[34:35], off offset:160
	global_load_dwordx4 v[160:163], v[34:35], off offset:176
	global_load_dwordx4 v[18:21], v[34:35], off
	global_load_dwordx4 v[22:25], v[34:35], off offset:16
	global_load_dwordx4 v[26:29], v[34:35], off offset:32
	global_load_dwordx4 v[30:33], v[34:35], off offset:48
	v_lshlrev_b32_e32 v37, 16, v10
	v_lshlrev_b32_e32 v36, 16, v14
	s_waitcnt vmcnt(3)
	v_pk_mul_f32 v[38:39], v[18:19], v[36:37] op_sel:[0,1] op_sel_hi:[1,0]
	v_pk_mul_f32 v[18:19], v[18:19], v[36:37]
	v_sub_f32_e32 v0, v38, v39
	v_add_f32_e32 v18, v18, v19
	v_mul_f32_e32 v38, 0x3dd53b94, v18
	v_and_b32_e32 v19, 0xffff0000, v10
	v_and_b32_e32 v18, 0xffff0000, v14
	v_pk_mul_f32 v[36:37], v[20:21], v[18:19] op_sel:[0,1] op_sel_hi:[1,0]
	v_pk_mul_f32 v[18:19], v[20:21], v[18:19]
	v_sub_f32_e32 v10, v36, v37
	v_mul_f32_e32 v36, 0x3dd53b94, v10
	v_add_f32_e32 v10, v18, v19
	v_lshlrev_b32_e32 v19, 16, v11
	v_lshlrev_b32_e32 v18, 16, v15
	s_waitcnt vmcnt(2)
	v_pk_mul_f32 v[20:21], v[22:23], v[18:19] op_sel:[0,1] op_sel_hi:[1,0]
	v_mul_f32_e32 v37, 0x3dd53b94, v10
	v_sub_f32_e32 v10, v20, v21
	v_pk_mul_f32 v[18:19], v[22:23], v[18:19]
	v_mul_f32_e32 v20, 0x3dd53b94, v10
	v_add_f32_e32 v10, v18, v19
	v_mul_f32_e32 v18, 0x3dd53b94, v10
	v_and_b32_e32 v11, 0xffff0000, v11
	v_and_b32_e32 v10, 0xffff0000, v15
	v_pk_mul_f32 v[14:15], v[24:25], v[10:11] op_sel:[0,1] op_sel_hi:[1,0]
	v_pk_mul_f32 v[10:11], v[24:25], v[10:11]
	v_sub_f32_e32 v14, v14, v15
	v_add_f32_e32 v10, v10, v11
	v_mul_f32_e32 v21, 0x3dd53b94, v10
	v_lshlrev_b32_e32 v11, 16, v12
	v_lshlrev_b32_e32 v10, 16, v16
	v_mul_f32_e32 v19, 0x3dd53b94, v14
	s_waitcnt vmcnt(1)
	v_pk_mul_f32 v[14:15], v[26:27], v[10:11] op_sel:[0,1] op_sel_hi:[1,0]
	v_pk_mul_f32 v[10:11], v[26:27], v[10:11]
	v_sub_f32_e32 v14, v14, v15
	v_add_f32_e32 v10, v10, v11
	v_mul_f32_e32 v23, 0x3dd53b94, v10
	v_and_b32_e32 v11, 0xffff0000, v12
	v_and_b32_e32 v10, 0xffff0000, v16
	v_mul_f32_e32 v22, 0x3dd53b94, v14
	v_pk_mul_f32 v[14:15], v[28:29], v[10:11] op_sel:[0,1] op_sel_hi:[1,0]
	v_pk_mul_f32 v[10:11], v[28:29], v[10:11]
	v_sub_f32_e32 v12, v14, v15
	v_add_f32_e32 v10, v10, v11
	v_mul_f32_e32 v24, 0x3dd53b94, v10
	v_lshlrev_b32_e32 v11, 16, v13
	v_lshlrev_b32_e32 v10, 16, v17
	s_waitcnt vmcnt(0)
	v_pk_mul_f32 v[14:15], v[30:31], v[10:11] op_sel:[0,1] op_sel_hi:[1,0]
	v_pk_mul_f32 v[10:11], v[30:31], v[10:11]
	v_mul_f32_e32 v16, 0x3dd53b94, v12
	v_add_f32_e32 v10, v10, v11
	v_sub_f32_e32 v12, v14, v15
	v_mul_f32_e32 v15, 0x3dd53b94, v10
	v_and_b32_e32 v11, 0xffff0000, v13
	v_and_b32_e32 v10, 0xffff0000, v17
	v_mul_f32_e32 v14, 0x3dd53b94, v12
	v_pk_mul_f32 v[12:13], v[32:33], v[10:11] op_sel:[0,1] op_sel_hi:[1,0]
	v_pk_mul_f32 v[10:11], v[32:33], v[10:11]
	v_sub_f32_e32 v12, v12, v13
	v_add_f32_e32 v10, v10, v11
	v_mul_f32_e32 v12, 0x3dd53b94, v12
	v_mul_f32_e32 v10, 0x3dd53b94, v10
	v_mul_f32_e32 v0, 0x3dd53b94, v0
	v_cvt_pk_bf16_f32 v144, v0, v36
	v_cvt_pk_bf16_f32 v145, v20, v19
	v_cvt_pk_bf16_f32 v146, v22, v16
	v_cvt_pk_bf16_f32 v147, v14, v12
	v_cvt_pk_bf16_f32 v148, v38, v37
	v_cvt_pk_bf16_f32 v149, v18, v21
	v_cvt_pk_bf16_f32 v150, v23, v24
	v_cvt_pk_bf16_f32 v151, v15, v10
	s_waitcnt vmcnt(0)
	v_mov_b32_e32 v10, v100
	v_mov_b32_e32 v11, v101
	v_mov_b32_e32 v12, v102
	v_mov_b32_e32 v13, v103
	v_mov_b32_e32 v14, v104
	v_mov_b32_e32 v15, v105
	v_mov_b32_e32 v16, v106
	v_mov_b32_e32 v17, v107
	v_mov_b32_e32 v18, v108
	v_mov_b32_e32 v19, v109
	v_mov_b32_e32 v20, v110
	v_mov_b32_e32 v21, v111
	v_mov_b32_e32 v22, v160
	v_mov_b32_e32 v23, v161
	v_mov_b32_e32 v24, v162
	v_mov_b32_e32 v25, v163
	v_lshlrev_b32_e32 v27, 16, v2
	v_lshlrev_b32_e32 v26, 16, v6
	s_waitcnt vmcnt(3)
	v_pk_mul_f32 v[28:29], v[10:11], v[26:27] op_sel:[0,1] op_sel_hi:[1,0]
	v_pk_mul_f32 v[10:11], v[10:11], v[26:27]
	v_sub_f32_e32 v0, v28, v29
	v_add_f32_e32 v10, v10, v11
	v_mul_f32_e32 v28, 0x3dd53b94, v10
	v_and_b32_e32 v11, 0xffff0000, v2
	v_and_b32_e32 v10, 0xffff0000, v6
	v_pk_mul_f32 v[26:27], v[12:13], v[10:11] op_sel:[0,1] op_sel_hi:[1,0]
	v_pk_mul_f32 v[10:11], v[12:13], v[10:11]
	v_sub_f32_e32 v2, v26, v27
	v_mul_f32_e32 v26, 0x3dd53b94, v2
	v_add_f32_e32 v2, v10, v11
	v_lshlrev_b32_e32 v11, 16, v3
	v_lshlrev_b32_e32 v10, 16, v7
	s_waitcnt vmcnt(2)
	v_pk_mul_f32 v[12:13], v[14:15], v[10:11] op_sel:[0,1] op_sel_hi:[1,0]
	v_mul_f32_e32 v27, 0x3dd53b94, v2
	v_sub_f32_e32 v2, v12, v13
	v_pk_mul_f32 v[10:11], v[14:15], v[10:11]
	v_mul_f32_e32 v12, 0x3dd53b94, v2
	v_add_f32_e32 v2, v10, v11
	v_mul_f32_e32 v10, 0x3dd53b94, v2
	v_and_b32_e32 v3, 0xffff0000, v3
	v_and_b32_e32 v2, 0xffff0000, v7
	v_pk_mul_f32 v[6:7], v[16:17], v[2:3] op_sel:[0,1] op_sel_hi:[1,0]
	v_pk_mul_f32 v[2:3], v[16:17], v[2:3]
	v_sub_f32_e32 v6, v6, v7
	v_add_f32_e32 v2, v2, v3
	v_mul_f32_e32 v13, 0x3dd53b94, v2
	v_lshlrev_b32_e32 v3, 16, v4
	v_lshlrev_b32_e32 v2, 16, v8
	v_mul_f32_e32 v11, 0x3dd53b94, v6
	s_waitcnt vmcnt(1)
	v_pk_mul_f32 v[6:7], v[18:19], v[2:3] op_sel:[0,1] op_sel_hi:[1,0]
	v_pk_mul_f32 v[2:3], v[18:19], v[2:3]
	v_sub_f32_e32 v6, v6, v7
	v_add_f32_e32 v2, v2, v3
	v_mul_f32_e32 v15, 0x3dd53b94, v2
	v_and_b32_e32 v3, 0xffff0000, v4
	v_and_b32_e32 v2, 0xffff0000, v8
	v_mul_f32_e32 v14, 0x3dd53b94, v6
	v_pk_mul_f32 v[6:7], v[20:21], v[2:3] op_sel:[0,1] op_sel_hi:[1,0]
	v_pk_mul_f32 v[2:3], v[20:21], v[2:3]
	v_sub_f32_e32 v4, v6, v7
	v_add_f32_e32 v2, v2, v3
	v_mul_f32_e32 v16, 0x3dd53b94, v2
	v_lshlrev_b32_e32 v3, 16, v5
	v_lshlrev_b32_e32 v2, 16, v9
	s_waitcnt vmcnt(0)
	v_pk_mul_f32 v[6:7], v[22:23], v[2:3] op_sel:[0,1] op_sel_hi:[1,0]
	v_pk_mul_f32 v[2:3], v[22:23], v[2:3]
	v_mul_f32_e32 v8, 0x3dd53b94, v4
	v_add_f32_e32 v2, v2, v3
	v_sub_f32_e32 v4, v6, v7
	v_mul_f32_e32 v7, 0x3dd53b94, v2
	v_and_b32_e32 v3, 0xffff0000, v5
	v_and_b32_e32 v2, 0xffff0000, v9
	v_mul_f32_e32 v6, 0x3dd53b94, v4
	v_pk_mul_f32 v[4:5], v[24:25], v[2:3] op_sel:[0,1] op_sel_hi:[1,0]
	v_pk_mul_f32 v[2:3], v[24:25], v[2:3]
	v_sub_f32_e32 v4, v4, v5
	v_mul_f32_e32 v0, 0x3dd53b94, v0
	v_mul_f32_e32 v4, 0x3dd53b94, v4
	v_add_f32_e32 v2, v2, v3
	v_cvt_pk_bf16_f32 v152, v0, v26
	v_cvt_pk_bf16_f32 v153, v12, v11
	v_cvt_pk_bf16_f32 v154, v14, v8
	v_cvt_pk_bf16_f32 v155, v6, v4
	v_cvt_pk_bf16_f32 v156, v28, v27
	v_cvt_pk_bf16_f32 v157, v10, v13
	v_mov_b32_e32 v10, v198
	v_mul_f32_e32 v2, 0x3dd53b94, v2
	v_cvt_pk_bf16_f32 v158, v15, v16
	v_cvt_pk_bf16_f32 v159, v7, v2
	s_nop 0
	v_readfirstlane_b32 s0, v10
	v_bfe_u32 v12, v10, 4, 2
	s_ashr_i32 s4, s0, 6
	v_and_b32_e32 v2, 15, v10
	v_bitop3_b32 v4, v12, v10, 15 bitop3:0x78
	s_lshl_b32 s0, s4, 3
	v_lshlrev_b32_e32 v13, 3, v4
	v_or_b32_e32 v4, 4, v12
	v_bitop3_b32 v2, v12, v2, 4 bitop3:0x36
	v_bfe_u32 v0, v10, 2, 3
	v_lshrrev_b32_e32 v3, 1, v10
	s_lshl_b32 s1, s4, 2
	v_or_b32_e32 v4, s0, v4
	v_lshlrev_b32_e32 v14, 3, v2
	v_bfe_u32 v15, v10, 3, 3
	v_bitop3_b32 v0, s0, v204, v0 bitop3:0xc8
	v_and_b32_e32 v3, 8, v3
	s_and_b32 s1, s1, 4
	v_lshl_or_b32 v2, v4, 12, v14
	v_or_b32_e32 v4, s0, v15
	v_or3_b32 v0, v3, v0, s1
	v_lshrrev_b32_e32 v6, 1, v4
	v_lshlrev_b32_e32 v11, 3, v10
	v_lshlrev_b32_e32 v8, 12, v0
	v_or_b32_e32 v0, s0, v12
	v_xor_b32_e32 v6, v6, v10
	s_lshl_b32 s5, s4, 11
	s_add_i32 s0, 0, 0x10000
	v_and_b32_e32 v3, 32, v10
	v_and_b32_e32 v5, 24, v11
	v_lshl_or_b32 v0, v0, 12, v13
	v_lshlrev_b32_e32 v6, 3, v6
	s_add_i32 s39, s0, s5
	v_and_b32_e32 v16, 56, v6
	v_lshl_add_u64 v[6:7], v[0:1], 1, s[14:15]
	s_mov_b32 m0, s39
	v_or3_b32 v170, v3, v5, v8
	global_load_lds_dwordx4 v[6:7], off
	v_lshl_add_u64 v[6:7], v[170:171], 1, s[14:15]
	s_add_i32 s40, s5, 0
	v_lshl_add_u64 v[8:9], v[6:7], 0, s[20:21]
	s_mov_b32 m0, s40
	s_or_b32 s18, s5, 0x400
	global_load_lds_dwordx4 v[8:9], off
	s_add_i32 m0, s0, s18
	s_mov_b64 s[0:1], 0x180
	v_mov_b32_e32 v3, v1
	v_lshl_add_u64 v[6:7], v[6:7], 0, s[0:1]
	s_lshl_b32 s0, s4, 10
	v_mul_lo_u32 v4, v4, s25
	v_lshl_add_u64 v[8:9], v[2:3], 1, s[14:15]
	s_add_i32 s0, s0, 0
	v_or_b32_e32 v4, v16, v4
	global_load_lds_dwordx4 v[8:9], off
	s_add_i32 m0, s40, 0x400
	v_mov_b32_e32 v5, v1
	s_add_i32 s41, s0, 0x1c000
	global_load_lds_dwordx4 v[6:7], off
	v_lshl_add_u64 v[6:7], v[4:5], 1, s[8:9]
	s_mov_b32 m0, s41
	v_add_u32_e32 v0, 0x40000, v0
	s_add_i32 s1, 0, 0x14000
	global_load_lds_dwordx4 v[6:7], off
	v_lshl_add_u64 v[6:7], v[0:1], 1, s[14:15]
	s_add_i32 m0, s1, s5
	v_add_u32_e32 v0, 0x40000, v170
	global_load_lds_dwordx4 v[6:7], off
	v_lshl_add_u64 v[6:7], v[0:1], 1, s[14:15]
	v_lshl_add_u64 v[6:7], v[6:7], 0, s[20:21]
	s_add_i32 m0, s40, 0x4000
	v_add_u32_e32 v0, 0x40000, v2
	global_load_lds_dwordx4 v[6:7], off
	v_lshl_add_u64 v[2:3], v[0:1], 1, s[14:15]
	s_add_i32 m0, s1, s18
	v_add_u32_e32 v0, 0x40040, v170
	global_load_lds_dwordx4 v[2:3], off
	s_add_i32 m0, s40, 0x4400
	v_lshl_add_u64 v[2:3], v[0:1], 1, s[14:15]
	s_cmp_gt_i32 s4, 3
	v_lshl_add_u64 v[2:3], v[2:3], 0, s[20:21]
	s_cselect_b64 s[18:19], -1, 0
	s_cmp_lt_i32 s4, 4
	v_add_u32_e32 v0, 0x44000, v4
	global_load_lds_dwordx4 v[2:3], off
	s_cselect_b64 s[20:21], -1, 0
	v_lshl_add_u64 v[2:3], v[0:1], 1, s[8:9]
	s_add_i32 m0, s0, 0x1e000
	v_and_b32_e32 v0, 63, v10
	global_load_lds_dwordx4 v[2:3], off
	v_and_b32_e32 v4, 0x3fffffc0, v10
	v_readlane_b32 s0, v254, 1
	v_lshlrev_b32_e32 v5, 4, v10
	v_bfe_u32 v3, v10, 5, 1
	v_lshl_add_u32 v176, v4, 2, s0
	v_lshlrev_b32_e32 v4, 3, v0
	v_and_b32_e32 v6, 0xc0, v5
	v_lshlrev_b32_e32 v7, 1, v10
	v_and_or_b32 v6, v4, 24, v6
	v_and_b32_e32 v7, 32, v7
	v_and_b32_e32 v4, 0x100, v4
	v_lshlrev_b32_e32 v177, 4, v3
	s_movk_i32 s0, 0x70
	v_or3_b32 v4, v6, v7, v4
	v_and_b32_e32 v6, 0x70, v5
	v_and_b32_e32 v7, 0x70, v11
	v_bitop3_b32 v185, v177, v5, s0 bitop3:0x78
	v_bitop3_b32 v187, v177, v11, s0 bitop3:0x78
	s_movk_i32 s0, 0x60
	s_lshl_b32 s5, s4, 15
	s_mul_i32 s4, s4, 0x8800
	v_bitop3_b32 v192, v177, v6, s0 bitop3:0x36
	v_bitop3_b32 v193, v177, v7, s0 bitop3:0x36
	v_cmp_gt_u32_e64 s[0:1], 32, v0
	s_add_i32 s24, s5, 0x84000
	v_lshlrev_b32_e32 v0, 12, v12
	s_add_i32 s5, s5, 0x80000
	s_add_i32 s4, s4, 0x88000
	v_or3_b32 v195, s24, v0, v14
	v_or3_b32 v196, s5, v0, v13
	v_mov_b32_e32 v0, s4
	v_and_b32_e32 v2, 31, v10
	s_waitcnt vmcnt(5)
	v_mad_u32_u24 v0, v15, s25, v0
	v_mov_b32_e32 v14, v1
	v_mov_b32_e32 v15, v1
	v_lshlrev_b32_e32 v183, 8, v2
	v_lshlrev_b32_e32 v184, 7, v2
	v_bitop3_b32 v188, v177, v6, 32 bitop3:0x36
	v_bitop3_b32 v189, v177, v7, 32 bitop3:0x36
	v_bitop3_b32 v190, v177, v6, 64 bitop3:0x36
	v_bitop3_b32 v191, v177, v7, 64 bitop3:0x36
	v_add_u32_e32 v171, 0, v4
	v_lshl_add_u32 v179, v2, 2, v176
	v_mad_i32_i24 v194, v3, -4, v175
	v_or_b32_e32 v172, v0, v16
	v_mov_b32_e32 v0, v1
	v_mov_b32_e32 v2, v1
	v_mov_b32_e32 v3, v1
	v_mov_b32_e32 v4, v1
	v_mov_b32_e32 v5, v1
	v_mov_b32_e32 v6, v1
	v_mov_b32_e32 v7, v1
	v_mov_b32_e32 v8, v1
	v_mov_b32_e32 v9, v1
	v_mov_b32_e32 v10, v1
	v_mov_b32_e32 v11, v1
	v_mov_b32_e32 v12, v1
	v_mov_b32_e32 v13, v1
	v_mov_b64_e32 v[30:31], v[14:15]
	v_mov_b64_e32 v[46:47], v[14:15]
	v_mov_b64_e32 v[62:63], v[14:15]
	v_mov_b64_e32 v[78:79], v[14:15]
	v_mov_b64_e32 v[94:95], v[14:15]
	v_mov_b64_e32 v[110:111], v[14:15]
	s_mov_b64 s[24:25], 0
	v_mov_b64_e32 v[28:29], v[12:13]
	v_mov_b64_e32 v[26:27], v[10:11]
	v_mov_b64_e32 v[24:25], v[8:9]
	v_mov_b64_e32 v[22:23], v[6:7]
	v_mov_b64_e32 v[20:21], v[4:5]
	v_mov_b64_e32 v[18:19], v[2:3]
	v_mov_b64_e32 v[16:17], v[0:1]
	v_mov_b64_e32 v[44:45], v[12:13]
	v_mov_b64_e32 v[42:43], v[10:11]
	v_mov_b64_e32 v[40:41], v[8:9]
	v_mov_b64_e32 v[38:39], v[6:7]
	v_mov_b64_e32 v[36:37], v[4:5]
	v_mov_b64_e32 v[34:35], v[2:3]
	v_mov_b64_e32 v[32:33], v[0:1]
	v_mov_b64_e32 v[60:61], v[12:13]
	v_mov_b64_e32 v[58:59], v[10:11]
	v_mov_b64_e32 v[56:57], v[8:9]
	v_mov_b64_e32 v[54:55], v[6:7]
	v_mov_b64_e32 v[52:53], v[4:5]
	v_mov_b64_e32 v[50:51], v[2:3]
	v_mov_b64_e32 v[48:49], v[0:1]
	v_mov_b64_e32 v[76:77], v[12:13]
	v_mov_b64_e32 v[74:75], v[10:11]
	v_mov_b64_e32 v[72:73], v[8:9]
	v_mov_b64_e32 v[70:71], v[6:7]
	v_mov_b64_e32 v[68:69], v[4:5]
	v_mov_b64_e32 v[66:67], v[2:3]
	v_mov_b64_e32 v[64:65], v[0:1]
	v_mov_b64_e32 v[92:93], v[12:13]
	v_mov_b64_e32 v[90:91], v[10:11]
	v_mov_b64_e32 v[88:89], v[8:9]
	v_mov_b64_e32 v[86:87], v[6:7]
	v_mov_b64_e32 v[84:85], v[4:5]
	v_mov_b64_e32 v[82:83], v[2:3]
	v_mov_b64_e32 v[80:81], v[0:1]
	v_mov_b64_e32 v[108:109], v[12:13]
	v_mov_b64_e32 v[106:107], v[10:11]
	v_mov_b64_e32 v[104:105], v[8:9]
	v_mov_b64_e32 v[102:103], v[6:7]
	v_mov_b64_e32 v[100:101], v[4:5]
	v_mov_b64_e32 v[98:99], v[2:3]
	v_mov_b64_e32 v[96:97], v[0:1]
	s_waitcnt vmcnt(5) lgkmcnt(0)
	s_barrier
	s_branch .LBB0_998

.LBB0_1033:
	s_ashr_i32 s4, s28, 3
	s_mul_hi_i32 s10, s4, 0x2aaaaaab
	s_lshr_b32 s5, s10, 31
	s_and_b32 s7, s28, 7
	s_add_i32 s10, s10, s5
	s_lshl_b32 s11, s10, 11
	s_lshl_b32 s6, s7, 8
	v_readlane_b32 s12, v252, 26
	s_mul_i32 s5, s10, 6
	s_or_b32 s9, s11, s6
	v_readlane_b32 s13, v252, 27
	s_sub_i32 s8, s4, s5
	v_add_u32_e32 v184, s9, v188
	v_mov_b64_e32 v[2:3], s[12:13]
	s_movk_i32 s4, 0x4400
	v_mad_i64_i32 v[2:3], s[4:5], v184, s4, v[2:3]
	s_lshl_b32 s4, s8, 7
	s_ashr_i32 s5, s4, 31
	s_lshl_b64 s[4:5], s[4:5], 1
	v_lshl_add_u64 v[2:3], v[2:3], 0, s[4:5]
	v_mov_b32_e32 v183, v1
	v_lshl_add_u64 v[6:7], v[2:3], 0, v[182:183]
	global_load_dwordx4 v[20:23], v[6:7], off
	global_load_dwordx4 v[24:27], v[6:7], off offset:128
	v_ashrrev_i32_e32 v185, 31, v184
	v_lshlrev_b64 v[2:3], 9, v[184:185]
	v_lshl_add_u64 v[18:19], v[148:149], 0, v[2:3]
	global_load_dwordx4 v[100:103], v[18:19], off offset:128
	global_load_dwordx4 v[104:107], v[18:19], off offset:144
	global_load_dwordx4 v[108:111], v[18:19], off offset:160
	global_load_dwordx4 v[144:147], v[18:19], off offset:176
	global_load_dwordx4 v[190:193], v[18:19], off offset:256
	global_load_dwordx4 v[194:197], v[18:19], off offset:272
	global_load_dwordx4 v[206:209], v[18:19], off offset:288
	global_load_dwordx4 v[210:213], v[18:19], off offset:304
	global_load_dwordx4 v[216:219], v[18:19], off offset:384
	global_load_dwordx4 v[220:223], v[18:19], off offset:400
	global_load_dwordx4 v[224:227], v[18:19], off offset:416
	global_load_dwordx4 v[228:231], v[18:19], off offset:432
	global_load_dwordx4 v[28:31], v[18:19], off
	global_load_dwordx4 v[32:35], v[18:19], off offset:16
	global_load_dwordx4 v[36:39], v[18:19], off offset:32
	global_load_dwordx4 v[40:43], v[18:19], off offset:48
	global_load_dwordx4 v[44:47], v[6:7], off offset:32
	global_load_dwordx4 v[10:13], v[6:7], off offset:64
	global_load_dwordx4 v[2:5], v[6:7], off offset:96
	global_load_dwordx4 v[48:51], v[6:7], off offset:160
	global_load_dwordx4 v[14:17], v[6:7], off offset:192
	s_nop 0
	global_load_dwordx4 v[6:9], v[6:7], off offset:224
	s_mul_i32 s10, s10, 0x2200000
	s_mul_hi_i32 s11, s11, 0x4400
	s_add_u32 s10, s12, s10
	s_addc_u32 s11, s13, s11
	s_add_u32 s4, s10, s4
	s_addc_u32 s5, s11, s5
	s_add_u32 s10, s4, 0x1200
	s_addc_u32 s11, s5, 0
	s_add_u32 s12, s4, 0x2400
	s_addc_u32 s13, s5, 0
	s_lshl_b32 s35, s7, 2
	s_add_i32 s4, s35, -2
	s_cmp_lg_u32 s7, 0
	s_cselect_b32 s29, s4, 0
	s_mul_i32 s30, s29, 0x88000
	s_add_i32 s35, s35, 4
	s_waitcnt vmcnt(11)
	v_lshlrev_b32_e32 v53, 16, v20
	s_waitcnt vmcnt(10)
	v_lshlrev_b32_e32 v52, 16, v24
	v_and_b32_e32 v55, 0xffff0000, v20
	v_and_b32_e32 v54, 0xffff0000, v24
	v_lshlrev_b32_e32 v57, 16, v21
	v_lshlrev_b32_e32 v56, 16, v25
	v_and_b32_e32 v21, 0xffff0000, v21
	v_and_b32_e32 v20, 0xffff0000, v25
	v_lshlrev_b32_e32 v25, 16, v22
	v_lshlrev_b32_e32 v24, 16, v26
	v_and_b32_e32 v59, 0xffff0000, v22
	v_and_b32_e32 v58, 0xffff0000, v26
	v_lshlrev_b32_e32 v60, 16, v27
	v_and_b32_e32 v22, 0xffff0000, v27
	s_waitcnt vmcnt(9)
	v_pk_mul_f32 v[26:27], v[28:29], v[52:53] op_sel:[0,1] op_sel_hi:[1,0]
	v_pk_mul_f32 v[28:29], v[28:29], v[52:53]
	v_pk_mul_f32 v[52:53], v[30:31], v[54:55] op_sel:[0,1] op_sel_hi:[1,0]
	v_pk_mul_f32 v[30:31], v[30:31], v[54:55]
	s_waitcnt vmcnt(8)
	v_pk_mul_f32 v[54:55], v[32:33], v[56:57] op_sel:[0,1] op_sel_hi:[1,0]
	v_pk_mul_f32 v[32:33], v[32:33], v[56:57]
	v_pk_mul_f32 v[56:57], v[34:35], v[20:21] op_sel:[0,1] op_sel_hi:[1,0]
	v_pk_mul_f32 v[20:21], v[34:35], v[20:21]
	s_waitcnt vmcnt(7)
	v_pk_mul_f32 v[34:35], v[36:37], v[24:25] op_sel:[0,1] op_sel_hi:[1,0]
	v_lshlrev_b32_e32 v61, 16, v23
	v_and_b32_e32 v23, 0xffff0000, v23
	v_pk_mul_f32 v[24:25], v[36:37], v[24:25]
	v_pk_mul_f32 v[36:37], v[38:39], v[58:59] op_sel:[0,1] op_sel_hi:[1,0]
	v_add_f32_e32 v20, v20, v21
	v_sub_f32_e32 v21, v34, v35
	v_pk_mul_f32 v[38:39], v[38:39], v[58:59]
	s_waitcnt vmcnt(6)
	v_pk_mul_f32 v[58:59], v[40:41], v[60:61] op_sel:[0,1] op_sel_hi:[1,0]
	v_pk_mul_f32 v[40:41], v[40:41], v[60:61]
	v_pk_mul_f32 v[60:61], v[42:43], v[22:23] op_sel:[0,1] op_sel_hi:[1,0]
	v_add_f32_e32 v24, v24, v25
	v_sub_f32_e32 v25, v36, v37
	v_mul_f32_e32 v36, 0x3e0293ee, v20
	v_mul_f32_e32 v37, 0x3e0293ee, v21
	v_pk_mul_f32 v[20:21], v[42:43], v[22:23]
	v_sub_f32_e32 v0, v26, v27
	v_add_f32_e32 v26, v28, v29
	v_sub_f32_e32 v27, v52, v53
	v_add_f32_e32 v28, v30, v31
	v_sub_f32_e32 v29, v54, v55
	v_add_f32_e32 v30, v32, v33
	v_sub_f32_e32 v31, v56, v57
	v_add_f32_e32 v32, v38, v39
	v_sub_f32_e32 v33, v58, v59
	v_add_f32_e32 v34, v40, v41
	v_sub_f32_e32 v35, v60, v61
	v_add_f32_e32 v20, v20, v21
	v_mul_f32_e32 v26, 0x3e0293ee, v26
	v_mul_f32_e32 v27, 0x3e0293ee, v27
	v_mul_f32_e32 v28, 0x3e0293ee, v28
	v_mul_f32_e32 v29, 0x3e0293ee, v29
	v_mul_f32_e32 v30, 0x3e0293ee, v30
	v_mul_f32_e32 v31, 0x3e0293ee, v31
	v_mul_f32_e32 v24, 0x3e0293ee, v24
	v_mul_f32_e32 v25, 0x3e0293ee, v25
	v_mul_f32_e32 v32, 0x3e0293ee, v32
	v_mul_f32_e32 v33, 0x3e0293ee, v33
	v_mul_f32_e32 v34, 0x3e0293ee, v34
	v_mul_f32_e32 v35, 0x3e0293ee, v35
	v_mul_f32_e32 v20, 0x3e0293ee, v20
	v_mul_f32_e32 v0, 0x3e0293ee, v0
	v_cvt_pk_bf16_f32 v112, v0, v27
	v_cvt_pk_bf16_f32 v113, v29, v31
	v_cvt_pk_bf16_f32 v114, v37, v25
	v_cvt_pk_bf16_f32 v115, v33, v35
	v_cvt_pk_bf16_f32 v116, v26, v28
	v_cvt_pk_bf16_f32 v117, v30, v36
	v_cvt_pk_bf16_f32 v118, v24, v32
	v_cvt_pk_bf16_f32 v119, v34, v20
	s_waitcnt vmcnt(0)
	v_mov_b32_e32 v20, v100
	v_mov_b32_e32 v21, v101
	v_mov_b32_e32 v22, v102
	v_mov_b32_e32 v23, v103
	v_mov_b32_e32 v24, v104
	v_mov_b32_e32 v25, v105
	v_mov_b32_e32 v26, v106
	v_mov_b32_e32 v27, v107
	v_mov_b32_e32 v28, v108
	v_mov_b32_e32 v29, v109
	v_mov_b32_e32 v30, v110
	v_mov_b32_e32 v31, v111
	v_mov_b32_e32 v32, v144
	v_mov_b32_e32 v33, v145
	v_mov_b32_e32 v34, v146
	v_mov_b32_e32 v35, v147
	s_waitcnt vmcnt(9)
	v_lshlrev_b32_e32 v37, 16, v44
	s_waitcnt vmcnt(6)
	v_lshlrev_b32_e32 v36, 16, v48
	v_and_b32_e32 v39, 0xffff0000, v44
	v_and_b32_e32 v38, 0xffff0000, v48
	v_lshlrev_b32_e32 v41, 16, v45
	v_lshlrev_b32_e32 v40, 16, v49
	v_and_b32_e32 v43, 0xffff0000, v45
	v_and_b32_e32 v42, 0xffff0000, v49
	v_lshlrev_b32_e32 v45, 16, v46
	v_lshlrev_b32_e32 v44, 16, v50
	v_and_b32_e32 v49, 0xffff0000, v46
	v_and_b32_e32 v48, 0xffff0000, v50
	v_lshlrev_b32_e32 v53, 16, v47
	v_lshlrev_b32_e32 v52, 16, v51
	v_and_b32_e32 v47, 0xffff0000, v47
	v_and_b32_e32 v46, 0xffff0000, v51
	s_waitcnt vmcnt(3)
	v_pk_mul_f32 v[50:51], v[20:21], v[36:37] op_sel:[0,1] op_sel_hi:[1,0]
	v_pk_mul_f32 v[20:21], v[20:21], v[36:37]
	v_pk_mul_f32 v[36:37], v[22:23], v[38:39] op_sel:[0,1] op_sel_hi:[1,0]
	v_pk_mul_f32 v[22:23], v[22:23], v[38:39]
	s_waitcnt vmcnt(2)
	v_pk_mul_f32 v[38:39], v[24:25], v[40:41] op_sel:[0,1] op_sel_hi:[1,0]
	v_pk_mul_f32 v[24:25], v[24:25], v[40:41]
	v_pk_mul_f32 v[40:41], v[26:27], v[42:43] op_sel:[0,1] op_sel_hi:[1,0]
	v_pk_mul_f32 v[26:27], v[26:27], v[42:43]
	s_waitcnt vmcnt(1)
	v_pk_mul_f32 v[42:43], v[28:29], v[44:45] op_sel:[0,1] op_sel_hi:[1,0]
	v_pk_mul_f32 v[28:29], v[28:29], v[44:45]
	v_pk_mul_f32 v[44:45], v[30:31], v[48:49] op_sel:[0,1] op_sel_hi:[1,0]
	v_pk_mul_f32 v[30:31], v[30:31], v[48:49]
	s_waitcnt vmcnt(0)
	v_pk_mul_f32 v[48:49], v[32:33], v[52:53] op_sel:[0,1] op_sel_hi:[1,0]
	v_pk_mul_f32 v[32:33], v[32:33], v[52:53]
	v_pk_mul_f32 v[52:53], v[34:35], v[46:47] op_sel:[0,1] op_sel_hi:[1,0]
	v_pk_mul_f32 v[34:35], v[34:35], v[46:47]
	v_add_f32_e32 v20, v20, v21
	v_sub_f32_e32 v21, v36, v37
	v_add_f32_e32 v22, v22, v23
	v_sub_f32_e32 v23, v38, v39
	v_add_f32_e32 v24, v24, v25
	v_sub_f32_e32 v25, v40, v41
	v_add_f32_e32 v26, v26, v27
	v_sub_f32_e32 v27, v42, v43
	v_add_f32_e32 v28, v28, v29
	v_sub_f32_e32 v29, v44, v45
	v_add_f32_e32 v30, v30, v31
	v_sub_f32_e32 v31, v48, v49
	v_add_f32_e32 v32, v32, v33
	v_sub_f32_e32 v33, v52, v53
	v_add_f32_e32 v34, v34, v35
	v_sub_f32_e32 v0, v50, v51
	v_mul_f32_e32 v20, 0x3e0293ee, v20
	v_mul_f32_e32 v21, 0x3e0293ee, v21
	v_mul_f32_e32 v22, 0x3e0293ee, v22
	v_mul_f32_e32 v23, 0x3e0293ee, v23
	v_mul_f32_e32 v24, 0x3e0293ee, v24
	v_mul_f32_e32 v25, 0x3e0293ee, v25
	v_mul_f32_e32 v26, 0x3e0293ee, v26
	v_mul_f32_e32 v27, 0x3e0293ee, v27
	v_mul_f32_e32 v28, 0x3e0293ee, v28
	v_mul_f32_e32 v29, 0x3e0293ee, v29
	v_mul_f32_e32 v30, 0x3e0293ee, v30
	v_mul_f32_e32 v31, 0x3e0293ee, v31
	v_mul_f32_e32 v32, 0x3e0293ee, v32
	v_mul_f32_e32 v33, 0x3e0293ee, v33
	v_mul_f32_e32 v34, 0x3e0293ee, v34
	v_mul_f32_e32 v0, 0x3e0293ee, v0
	v_cvt_pk_bf16_f32 v120, v0, v21
	v_cvt_pk_bf16_f32 v121, v23, v25
	v_cvt_pk_bf16_f32 v122, v27, v29
	v_cvt_pk_bf16_f32 v123, v31, v33
	v_cvt_pk_bf16_f32 v124, v20, v22
	v_cvt_pk_bf16_f32 v125, v24, v26
	v_cvt_pk_bf16_f32 v126, v28, v30
	v_cvt_pk_bf16_f32 v127, v32, v34
	s_waitcnt vmcnt(0)
	v_mov_b32_e32 v20, v190
	v_mov_b32_e32 v21, v191
	v_mov_b32_e32 v22, v192
	v_mov_b32_e32 v23, v193
	v_mov_b32_e32 v24, v194
	v_mov_b32_e32 v25, v195
	v_mov_b32_e32 v26, v196
	v_mov_b32_e32 v27, v197
	v_mov_b32_e32 v28, v206
	v_mov_b32_e32 v29, v207
	v_mov_b32_e32 v30, v208
	v_mov_b32_e32 v31, v209
	v_mov_b32_e32 v32, v210
	v_mov_b32_e32 v33, v211
	v_mov_b32_e32 v34, v212
	v_mov_b32_e32 v35, v213
	v_lshlrev_b32_e32 v37, 16, v10
	v_lshlrev_b32_e32 v36, 16, v14
	v_and_b32_e32 v39, 0xffff0000, v10
	v_and_b32_e32 v38, 0xffff0000, v14
	v_lshlrev_b32_e32 v41, 16, v11
	v_lshlrev_b32_e32 v40, 16, v15
	v_and_b32_e32 v11, 0xffff0000, v11
	v_and_b32_e32 v10, 0xffff0000, v15
	v_lshlrev_b32_e32 v15, 16, v12
	v_lshlrev_b32_e32 v14, 16, v16
	v_and_b32_e32 v43, 0xffff0000, v12
	v_and_b32_e32 v42, 0xffff0000, v16
	v_lshlrev_b32_e32 v45, 16, v13
	v_lshlrev_b32_e32 v44, 16, v17
	v_and_b32_e32 v13, 0xffff0000, v13
	v_and_b32_e32 v12, 0xffff0000, v17
	s_waitcnt vmcnt(3)
	v_pk_mul_f32 v[16:17], v[20:21], v[36:37] op_sel:[0,1] op_sel_hi:[1,0]
	v_pk_mul_f32 v[20:21], v[20:21], v[36:37]
	v_pk_mul_f32 v[36:37], v[22:23], v[38:39] op_sel:[0,1] op_sel_hi:[1,0]
	v_pk_mul_f32 v[22:23], v[22:23], v[38:39]
	s_waitcnt vmcnt(2)
	v_pk_mul_f32 v[38:39], v[24:25], v[40:41] op_sel:[0,1] op_sel_hi:[1,0]
	v_pk_mul_f32 v[24:25], v[24:25], v[40:41]
	v_pk_mul_f32 v[40:41], v[26:27], v[10:11] op_sel:[0,1] op_sel_hi:[1,0]
	v_pk_mul_f32 v[10:11], v[26:27], v[10:11]
	s_waitcnt vmcnt(1)
	v_pk_mul_f32 v[26:27], v[28:29], v[14:15] op_sel:[0,1] op_sel_hi:[1,0]
	v_pk_mul_f32 v[14:15], v[28:29], v[14:15]
	v_pk_mul_f32 v[28:29], v[30:31], v[42:43] op_sel:[0,1] op_sel_hi:[1,0]
	v_pk_mul_f32 v[30:31], v[30:31], v[42:43]
	s_waitcnt vmcnt(0)
	v_pk_mul_f32 v[42:43], v[32:33], v[44:45] op_sel:[0,1] op_sel_hi:[1,0]
	v_pk_mul_f32 v[32:33], v[32:33], v[44:45]
	v_pk_mul_f32 v[44:45], v[34:35], v[12:13] op_sel:[0,1] op_sel_hi:[1,0]
	v_pk_mul_f32 v[12:13], v[34:35], v[12:13]
	v_sub_f32_e32 v0, v16, v17
	v_add_f32_e32 v16, v20, v21
	v_sub_f32_e32 v17, v36, v37
	v_add_f32_e32 v20, v22, v23
	v_sub_f32_e32 v21, v38, v39
	v_add_f32_e32 v22, v24, v25
	v_sub_f32_e32 v23, v40, v41
	v_add_f32_e32 v10, v10, v11
	v_sub_f32_e32 v11, v26, v27
	v_add_f32_e32 v14, v14, v15
	v_sub_f32_e32 v15, v28, v29
	v_add_f32_e32 v24, v30, v31
	v_sub_f32_e32 v25, v42, v43
	v_add_f32_e32 v26, v32, v33
	v_sub_f32_e32 v27, v44, v45
	v_add_f32_e32 v12, v12, v13
	v_mul_f32_e32 v13, 0x3e0293ee, v16
	v_mul_f32_e32 v16, 0x3e0293ee, v17
	v_mul_f32_e32 v17, 0x3e0293ee, v20
	v_mul_f32_e32 v20, 0x3e0293ee, v21
	v_mul_f32_e32 v21, 0x3e0293ee, v22
	v_mul_f32_e32 v22, 0x3e0293ee, v23
	v_mul_f32_e32 v10, 0x3e0293ee, v10
	v_mul_f32_e32 v11, 0x3e0293ee, v11
	v_mul_f32_e32 v14, 0x3e0293ee, v14
	v_mul_f32_e32 v15, 0x3e0293ee, v15
	v_mul_f32_e32 v23, 0x3e0293ee, v24
	v_mul_f32_e32 v24, 0x3e0293ee, v25
	v_mul_f32_e32 v25, 0x3e0293ee, v26
	v_mul_f32_e32 v26, 0x3e0293ee, v27
	v_mul_f32_e32 v12, 0x3e0293ee, v12
	v_mul_f32_e32 v0, 0x3e0293ee, v0
	v_cvt_pk_bf16_f32 v128, v0, v16
	v_cvt_pk_bf16_f32 v129, v20, v22
	v_cvt_pk_bf16_f32 v130, v11, v15
	v_cvt_pk_bf16_f32 v131, v24, v26
	v_cvt_pk_bf16_f32 v132, v13, v17
	v_cvt_pk_bf16_f32 v133, v21, v10
	v_cvt_pk_bf16_f32 v134, v14, v23
	v_cvt_pk_bf16_f32 v135, v25, v12
	s_waitcnt vmcnt(0)
	v_mov_b32_e32 v10, v216
	v_mov_b32_e32 v11, v217
	v_mov_b32_e32 v12, v218
	v_mov_b32_e32 v13, v219
	v_mov_b32_e32 v14, v220
	v_mov_b32_e32 v15, v221
	v_mov_b32_e32 v16, v222
	v_mov_b32_e32 v17, v223
	v_mov_b32_e32 v20, v224
	v_mov_b32_e32 v21, v225
	v_mov_b32_e32 v22, v226
	v_mov_b32_e32 v23, v227
	v_mov_b32_e32 v24, v228
	v_mov_b32_e32 v25, v229
	v_mov_b32_e32 v26, v230
	v_mov_b32_e32 v27, v231
	v_lshlrev_b32_e32 v19, 16, v2
	v_lshlrev_b32_e32 v18, 16, v6
	v_and_b32_e32 v29, 0xffff0000, v2
	v_and_b32_e32 v28, 0xffff0000, v6
	v_lshlrev_b32_e32 v31, 16, v3
	v_lshlrev_b32_e32 v30, 16, v7
	v_and_b32_e32 v3, 0xffff0000, v3
	v_and_b32_e32 v2, 0xffff0000, v7
	v_lshlrev_b32_e32 v7, 16, v4
	v_lshlrev_b32_e32 v6, 16, v8
	v_and_b32_e32 v33, 0xffff0000, v4
	v_and_b32_e32 v32, 0xffff0000, v8
	v_lshlrev_b32_e32 v35, 16, v5
	v_lshlrev_b32_e32 v34, 16, v9
	v_and_b32_e32 v5, 0xffff0000, v5
	v_and_b32_e32 v4, 0xffff0000, v9
	s_waitcnt vmcnt(3)
	v_pk_mul_f32 v[8:9], v[10:11], v[18:19] op_sel:[0,1] op_sel_hi:[1,0]
	v_pk_mul_f32 v[10:11], v[10:11], v[18:19]
	v_pk_mul_f32 v[18:19], v[12:13], v[28:29] op_sel:[0,1] op_sel_hi:[1,0]
	v_pk_mul_f32 v[12:13], v[12:13], v[28:29]
	s_waitcnt vmcnt(2)
	v_pk_mul_f32 v[28:29], v[14:15], v[30:31] op_sel:[0,1] op_sel_hi:[1,0]
	v_pk_mul_f32 v[14:15], v[14:15], v[30:31]
	v_pk_mul_f32 v[30:31], v[16:17], v[2:3] op_sel:[0,1] op_sel_hi:[1,0]
	v_pk_mul_f32 v[2:3], v[16:17], v[2:3]
	s_waitcnt vmcnt(1)
	v_pk_mul_f32 v[16:17], v[20:21], v[6:7] op_sel:[0,1] op_sel_hi:[1,0]
	v_pk_mul_f32 v[6:7], v[20:21], v[6:7]
	v_pk_mul_f32 v[20:21], v[22:23], v[32:33] op_sel:[0,1] op_sel_hi:[1,0]
	v_pk_mul_f32 v[22:23], v[22:23], v[32:33]
	s_waitcnt vmcnt(0)
	v_pk_mul_f32 v[32:33], v[24:25], v[34:35] op_sel:[0,1] op_sel_hi:[1,0]
	v_pk_mul_f32 v[24:25], v[24:25], v[34:35]
	v_pk_mul_f32 v[34:35], v[26:27], v[4:5] op_sel:[0,1] op_sel_hi:[1,0]
	v_pk_mul_f32 v[4:5], v[26:27], v[4:5]
	v_sub_f32_e32 v0, v8, v9
	v_add_f32_e32 v8, v10, v11
	v_sub_f32_e32 v9, v18, v19
	v_add_f32_e32 v10, v12, v13
	v_sub_f32_e32 v11, v28, v29
	v_add_f32_e32 v12, v14, v15
	v_sub_f32_e32 v13, v30, v31
	v_add_f32_e32 v2, v2, v3
	v_sub_f32_e32 v3, v16, v17
	v_add_f32_e32 v6, v6, v7
	v_sub_f32_e32 v7, v20, v21
	v_add_f32_e32 v14, v22, v23
	v_sub_f32_e32 v15, v32, v33
	v_add_f32_e32 v16, v24, v25
	v_sub_f32_e32 v17, v34, v35
	v_add_f32_e32 v4, v4, v5
	v_mul_f32_e32 v5, 0x3e0293ee, v8
	v_mul_f32_e32 v8, 0x3e0293ee, v9
	v_mul_f32_e32 v9, 0x3e0293ee, v10
	v_mul_f32_e32 v0, 0x3e0293ee, v0
	v_mul_f32_e32 v10, 0x3e0293ee, v11
	v_mul_f32_e32 v11, 0x3e0293ee, v12
	v_mul_f32_e32 v12, 0x3e0293ee, v13
	v_mul_f32_e32 v3, 0x3e0293ee, v3
	v_mul_f32_e32 v7, 0x3e0293ee, v7
	v_mul_f32_e32 v13, 0x3e0293ee, v14
	v_mul_f32_e32 v14, 0x3e0293ee, v15
	v_mul_f32_e32 v15, 0x3e0293ee, v16
	v_mul_f32_e32 v16, 0x3e0293ee, v17
	v_cvt_pk_bf16_f32 v136, v0, v8
	v_cvt_pk_bf16_f32 v137, v10, v12
	v_cvt_pk_bf16_f32 v138, v3, v7
	v_cvt_pk_bf16_f32 v139, v14, v16
	v_cvt_pk_bf16_f32 v140, v5, v9
	v_mov_b32_e32 v9, v198
	v_mul_f32_e32 v2, 0x3e0293ee, v2
	v_mul_f32_e32 v6, 0x3e0293ee, v6
	v_mul_f32_e32 v4, 0x3e0293ee, v4
	v_cvt_pk_bf16_f32 v141, v11, v2
	v_cvt_pk_bf16_f32 v142, v6, v13
	v_cvt_pk_bf16_f32 v143, v15, v4
	s_nop 0
	v_readfirstlane_b32 s4, v9
	s_ashr_i32 s7, s4, 6
	s_lshl_b32 s4, s7, 3
	v_bfe_u32 v3, v9, 2, 3
	v_lshrrev_b32_e32 v4, 1, v9
	s_lshl_b32 s5, s7, 2
	v_bitop3_b32 v3, s4, -13, v3 bitop3:0xc8
	v_and_b32_e32 v5, 8, v4
	s_and_b32 s18, s5, 4
	v_or3_b32 v4, v5, v3, s18
	v_lshlrev_b32_e32 v7, 3, v9
	s_movk_i32 s5, 0x2200
	v_bfe_u32 v2, v9, 4, 2
	v_and_b32_e32 v6, 32, v9
	v_and_b32_e32 v7, 24, v7
	v_mul_lo_u32 v4, v4, s5
	v_or3_b32 v11, v6, v7, v4
	v_or_b32_e32 v8, s4, v2
	v_bitop3_b32 v4, v2, v9, 15 bitop3:0x78
	v_lshlrev_b32_e32 v4, 3, v4
	v_mul_lo_u32 v8, v8, s5
	v_and_b32_e32 v0, 15, v9
	v_or_b32_e32 v13, v8, v4
	v_or_b32_e32 v8, 4, v2
	v_or_b32_e32 v10, s4, v8
	v_bitop3_b32 v0, v2, v0, 4 bitop3:0x36
	v_lshlrev_b32_e32 v8, 3, v0
	v_mul_lo_u32 v0, v10, s5
	s_lshl_b32 s14, s7, 11
	s_add_i32 s4, 0, 0x10000
	v_or_b32_e32 v12, v0, v8
	v_add_u32_e32 v0, s30, v13
	s_add_i32 s31, s4, s14
	v_lshl_add_u64 v[14:15], v[0:1], 1, s[10:11]
	s_mov_b32 m0, s31
	v_add_u32_e32 v0, s30, v11
	s_add_i32 s34, s14, 0
	v_or_b32_e32 v10, 64, v11
	global_load_lds_dwordx4 v[14:15], off
	v_lshl_add_u64 v[14:15], v[0:1], 1, s[12:13]
	s_mov_b32 m0, s34
	v_add_u32_e32 v0, s30, v12
	s_or_b32 s15, s14, 0x400
	global_load_lds_dwordx4 v[14:15], off
	v_lshl_add_u64 v[14:15], v[0:1], 1, s[10:11]
	s_add_i32 m0, s4, s15
	v_add_u32_e32 v0, s30, v10
	global_load_lds_dwordx4 v[14:15], off
	v_lshl_add_u64 v[14:15], v[0:1], 1, s[12:13]
	s_add_i32 m0, s34, 0x400
	s_or_b32 s4, s29, 1
	global_load_lds_dwordx4 v[14:15], off
	s_cmp_ge_u32 s4, s35
	s_mov_b64 s[4:5], -1
	s_cbranch_scc0 .LBB0_1035
	s_waitcnt vmcnt(0)
	s_mov_b64 s[4:5], 0

.LBB0_1074:
	s_xor_b64 s[12:13], s[0:1], -1
	s_and_b64 s[0:1], s[0:1], exec
	s_cselect_b32 s19, s31, s30
	s_lshl_b32 s18, s19, 8
	s_or_b32 s2, s18, s34
	v_add_u32_e32 v18, s2, v162
	s_movk_i32 s0, 0x3400
	v_mad_i64_i32 v[6:7], s[0:1], v18, s0, v[156:157]
	global_load_dwordx4 v[22:25], v[6:7], off
	global_load_dwordx4 v[26:29], v[6:7], off offset:128
	v_ashrrev_i32_e32 v19, 31, v18
	v_lshlrev_b64 v[2:3], 9, v[18:19]
	v_lshl_add_u64 v[20:21], v[154:155], 0, v[2:3]
	global_load_dwordx4 v[100:103], v[20:21], off offset:128
	global_load_dwordx4 v[104:107], v[20:21], off offset:144
	global_load_dwordx4 v[108:111], v[20:21], off offset:160
	global_load_dwordx4 v[148:151], v[20:21], off offset:176
	global_load_dwordx4 v[166:169], v[20:21], off offset:256
	global_load_dwordx4 v[170:173], v[20:21], off offset:272
	global_load_dwordx4 v[180:183], v[20:21], off offset:288
	global_load_dwordx4 v[184:187], v[20:21], off offset:304
	global_load_dwordx4 v[188:191], v[20:21], off offset:384
	global_load_dwordx4 v[192:195], v[20:21], off offset:400
	global_load_dwordx4 v[206:209], v[20:21], off offset:416
	global_load_dwordx4 v[210:213], v[20:21], off offset:432
	global_load_dwordx4 v[30:33], v[20:21], off
	global_load_dwordx4 v[34:37], v[20:21], off offset:16
	global_load_dwordx4 v[38:41], v[20:21], off offset:32
	global_load_dwordx4 v[42:45], v[20:21], off offset:48
	global_load_dwordx4 v[46:49], v[6:7], off offset:32
	global_load_dwordx4 v[10:13], v[6:7], off offset:64
	global_load_dwordx4 v[2:5], v[6:7], off offset:96
	global_load_dwordx4 v[50:53], v[6:7], off offset:160
	global_load_dwordx4 v[14:17], v[6:7], off offset:192
	s_nop 0
	global_load_dwordx4 v[6:9], v[6:7], off offset:224
	v_mov_b32_e32 v159, v1
	v_lshlrev_b64 v[18:19], 8, v[18:19]
	v_lshl_add_u64 v[18:19], s[90:91], 0, v[18:19]
	s_lshl_b32 s37, s19, 2
	s_add_i32 s37, s37, 4
	s_mul_i32 s38, s19, 0x1a0000
	s_mov_b32 s39, 0
	v_mov_b32_e32 v179, 0
	v_mov_b32_e32 v177, 0xf149f2ca
	s_mov_b32 s40, 0
	s_mov_b32 s41, 0
	s_mov_b32 s42, 0
	s_mov_b32 s43, 0
	s_waitcnt vmcnt(11)
	v_lshlrev_b32_e32 v55, 16, v22
	s_waitcnt vmcnt(10)
	v_lshlrev_b32_e32 v54, 16, v26
	v_and_b32_e32 v57, 0xffff0000, v22
	v_and_b32_e32 v56, 0xffff0000, v26
	v_lshlrev_b32_e32 v59, 16, v23
	v_lshlrev_b32_e32 v58, 16, v27
	v_and_b32_e32 v23, 0xffff0000, v23
	v_and_b32_e32 v22, 0xffff0000, v27
	v_lshlrev_b32_e32 v27, 16, v24
	v_lshlrev_b32_e32 v26, 16, v28
	v_and_b32_e32 v61, 0xffff0000, v24
	v_and_b32_e32 v60, 0xffff0000, v28
	v_lshlrev_b32_e32 v63, 16, v25
	v_lshlrev_b32_e32 v62, 16, v29
	v_and_b32_e32 v25, 0xffff0000, v25
	v_and_b32_e32 v24, 0xffff0000, v29
	s_waitcnt vmcnt(9)
	v_pk_mul_f32 v[28:29], v[30:31], v[54:55] op_sel:[0,1] op_sel_hi:[1,0]
	v_pk_mul_f32 v[30:31], v[30:31], v[54:55]
	v_pk_mul_f32 v[54:55], v[32:33], v[56:57] op_sel:[0,1] op_sel_hi:[1,0]
	v_pk_mul_f32 v[32:33], v[32:33], v[56:57]
	s_waitcnt vmcnt(8)
	v_pk_mul_f32 v[56:57], v[34:35], v[58:59] op_sel:[0,1] op_sel_hi:[1,0]
	v_pk_mul_f32 v[34:35], v[34:35], v[58:59]
	v_pk_mul_f32 v[58:59], v[36:37], v[22:23] op_sel:[0,1] op_sel_hi:[1,0]
	v_pk_mul_f32 v[22:23], v[36:37], v[22:23]
	s_waitcnt vmcnt(7)
	v_pk_mul_f32 v[36:37], v[38:39], v[26:27] op_sel:[0,1] op_sel_hi:[1,0]
	v_pk_mul_f32 v[26:27], v[38:39], v[26:27]
	v_pk_mul_f32 v[38:39], v[40:41], v[60:61] op_sel:[0,1] op_sel_hi:[1,0]
	v_pk_mul_f32 v[40:41], v[40:41], v[60:61]
	s_waitcnt vmcnt(6)
	v_pk_mul_f32 v[60:61], v[42:43], v[62:63] op_sel:[0,1] op_sel_hi:[1,0]
	v_pk_mul_f32 v[42:43], v[42:43], v[62:63]
	v_pk_mul_f32 v[62:63], v[44:45], v[24:25] op_sel:[0,1] op_sel_hi:[1,0]
	v_pk_mul_f32 v[24:25], v[44:45], v[24:25]
	v_sub_f32_e32 v0, v28, v29
	v_add_f32_e32 v28, v30, v31
	v_sub_f32_e32 v29, v54, v55
	v_add_f32_e32 v30, v32, v33
	v_sub_f32_e32 v31, v56, v57
	v_add_f32_e32 v32, v34, v35
	v_sub_f32_e32 v33, v58, v59
	v_add_f32_e32 v22, v22, v23
	v_sub_f32_e32 v23, v36, v37
	v_add_f32_e32 v26, v26, v27
	v_sub_f32_e32 v27, v38, v39
	v_add_f32_e32 v34, v40, v41
	v_sub_f32_e32 v35, v60, v61
	v_add_f32_e32 v36, v42, v43
	v_sub_f32_e32 v37, v62, v63
	v_add_f32_e32 v24, v24, v25
	v_mul_f32_e32 v25, 0x3e0293ee, v28
	v_mul_f32_e32 v28, 0x3e0293ee, v29
	v_mul_f32_e32 v29, 0x3e0293ee, v30
	v_mul_f32_e32 v30, 0x3e0293ee, v31
	v_mul_f32_e32 v31, 0x3e0293ee, v32
	v_mul_f32_e32 v32, 0x3e0293ee, v33
	v_mul_f32_e32 v22, 0x3e0293ee, v22
	v_mul_f32_e32 v23, 0x3e0293ee, v23
	v_mul_f32_e32 v26, 0x3e0293ee, v26
	v_mul_f32_e32 v27, 0x3e0293ee, v27
	v_mul_f32_e32 v33, 0x3e0293ee, v34
	v_mul_f32_e32 v34, 0x3e0293ee, v35
	v_mul_f32_e32 v35, 0x3e0293ee, v36
	v_mul_f32_e32 v36, 0x3e0293ee, v37
	v_mul_f32_e32 v24, 0x3e0293ee, v24
	v_mul_f32_e32 v0, 0x3e0293ee, v0
	v_cvt_pk_bf16_f32 v112, v0, v28
	v_cvt_pk_bf16_f32 v113, v30, v32
	v_cvt_pk_bf16_f32 v114, v23, v27
	v_cvt_pk_bf16_f32 v115, v34, v36
	v_cvt_pk_bf16_f32 v116, v25, v29
	v_cvt_pk_bf16_f32 v117, v31, v22
	v_cvt_pk_bf16_f32 v118, v26, v33
	v_cvt_pk_bf16_f32 v119, v35, v24
	s_waitcnt vmcnt(0)
	v_mov_b32_e32 v22, v100
	v_mov_b32_e32 v23, v101
	v_mov_b32_e32 v24, v102
	v_mov_b32_e32 v25, v103
	v_mov_b32_e32 v26, v104
	v_mov_b32_e32 v27, v105
	v_mov_b32_e32 v28, v106
	v_mov_b32_e32 v29, v107
	v_mov_b32_e32 v30, v108
	v_mov_b32_e32 v31, v109
	v_mov_b32_e32 v32, v110
	v_mov_b32_e32 v33, v111
	v_mov_b32_e32 v34, v148
	v_mov_b32_e32 v35, v149
	v_mov_b32_e32 v36, v150
	v_mov_b32_e32 v37, v151
	s_waitcnt vmcnt(9)
	v_lshlrev_b32_e32 v39, 16, v46
	s_waitcnt vmcnt(6)
	v_lshlrev_b32_e32 v38, 16, v50
	v_and_b32_e32 v41, 0xffff0000, v46
	v_and_b32_e32 v40, 0xffff0000, v50
	v_lshlrev_b32_e32 v43, 16, v47
	v_lshlrev_b32_e32 v42, 16, v51
	v_and_b32_e32 v45, 0xffff0000, v47
	v_and_b32_e32 v44, 0xffff0000, v51
	v_lshlrev_b32_e32 v47, 16, v48
	v_lshlrev_b32_e32 v46, 16, v52
	v_and_b32_e32 v51, 0xffff0000, v48
	v_and_b32_e32 v50, 0xffff0000, v52
	v_lshlrev_b32_e32 v55, 16, v49
	v_lshlrev_b32_e32 v54, 16, v53
	v_and_b32_e32 v49, 0xffff0000, v49
	v_and_b32_e32 v48, 0xffff0000, v53
	s_waitcnt vmcnt(3)
	v_pk_mul_f32 v[52:53], v[22:23], v[38:39] op_sel:[0,1] op_sel_hi:[1,0]
	v_pk_mul_f32 v[22:23], v[22:23], v[38:39]
	v_pk_mul_f32 v[38:39], v[24:25], v[40:41] op_sel:[0,1] op_sel_hi:[1,0]
	v_pk_mul_f32 v[24:25], v[24:25], v[40:41]
	s_waitcnt vmcnt(2)
	v_pk_mul_f32 v[40:41], v[26:27], v[42:43] op_sel:[0,1] op_sel_hi:[1,0]
	v_pk_mul_f32 v[26:27], v[26:27], v[42:43]
	v_pk_mul_f32 v[42:43], v[28:29], v[44:45] op_sel:[0,1] op_sel_hi:[1,0]
	v_pk_mul_f32 v[28:29], v[28:29], v[44:45]
	s_waitcnt vmcnt(1)
	v_pk_mul_f32 v[44:45], v[30:31], v[46:47] op_sel:[0,1] op_sel_hi:[1,0]
	v_pk_mul_f32 v[30:31], v[30:31], v[46:47]
	v_pk_mul_f32 v[46:47], v[32:33], v[50:51] op_sel:[0,1] op_sel_hi:[1,0]
	v_pk_mul_f32 v[32:33], v[32:33], v[50:51]
	s_waitcnt vmcnt(0)
	v_pk_mul_f32 v[50:51], v[34:35], v[54:55] op_sel:[0,1] op_sel_hi:[1,0]
	v_pk_mul_f32 v[34:35], v[34:35], v[54:55]
	v_pk_mul_f32 v[54:55], v[36:37], v[48:49] op_sel:[0,1] op_sel_hi:[1,0]
	v_pk_mul_f32 v[36:37], v[36:37], v[48:49]
	v_add_f32_e32 v22, v22, v23
	v_sub_f32_e32 v23, v38, v39
	v_add_f32_e32 v24, v24, v25
	v_sub_f32_e32 v25, v40, v41
	v_add_f32_e32 v26, v26, v27
	v_sub_f32_e32 v27, v42, v43
	v_add_f32_e32 v28, v28, v29
	v_sub_f32_e32 v29, v44, v45
	v_add_f32_e32 v30, v30, v31
	v_sub_f32_e32 v31, v46, v47
	v_add_f32_e32 v32, v32, v33
	v_sub_f32_e32 v33, v50, v51
	v_add_f32_e32 v34, v34, v35
	v_sub_f32_e32 v35, v54, v55
	v_add_f32_e32 v36, v36, v37
	v_sub_f32_e32 v0, v52, v53
	v_mul_f32_e32 v22, 0x3e0293ee, v22
	v_mul_f32_e32 v23, 0x3e0293ee, v23
	v_mul_f32_e32 v24, 0x3e0293ee, v24
	v_mul_f32_e32 v25, 0x3e0293ee, v25
	v_mul_f32_e32 v26, 0x3e0293ee, v26
	v_mul_f32_e32 v27, 0x3e0293ee, v27
	v_mul_f32_e32 v28, 0x3e0293ee, v28
	v_mul_f32_e32 v29, 0x3e0293ee, v29
	v_mul_f32_e32 v30, 0x3e0293ee, v30
	v_mul_f32_e32 v31, 0x3e0293ee, v31
	v_mul_f32_e32 v32, 0x3e0293ee, v32
	v_mul_f32_e32 v33, 0x3e0293ee, v33
	v_mul_f32_e32 v34, 0x3e0293ee, v34
	v_mul_f32_e32 v35, 0x3e0293ee, v35
	v_mul_f32_e32 v36, 0x3e0293ee, v36
	v_mul_f32_e32 v0, 0x3e0293ee, v0
	v_cvt_pk_bf16_f32 v120, v0, v23
	v_cvt_pk_bf16_f32 v121, v25, v27
	v_cvt_pk_bf16_f32 v122, v29, v31
	v_cvt_pk_bf16_f32 v123, v33, v35
	v_cvt_pk_bf16_f32 v124, v22, v24
	v_cvt_pk_bf16_f32 v125, v26, v28
	v_cvt_pk_bf16_f32 v126, v30, v32
	v_cvt_pk_bf16_f32 v127, v34, v36
	s_waitcnt vmcnt(0)
	v_mov_b32_e32 v22, v166
	v_mov_b32_e32 v23, v167
	v_mov_b32_e32 v24, v168
	v_mov_b32_e32 v25, v169
	v_mov_b32_e32 v26, v170
	v_mov_b32_e32 v27, v171
	v_mov_b32_e32 v28, v172
	v_mov_b32_e32 v29, v173
	v_mov_b32_e32 v30, v180
	v_mov_b32_e32 v31, v181
	v_mov_b32_e32 v32, v182
	v_mov_b32_e32 v33, v183
	v_mov_b32_e32 v34, v184
	v_mov_b32_e32 v35, v185
	v_mov_b32_e32 v36, v186
	v_mov_b32_e32 v37, v187
	v_lshlrev_b32_e32 v39, 16, v10
	v_lshlrev_b32_e32 v38, 16, v14
	v_and_b32_e32 v41, 0xffff0000, v10
	v_and_b32_e32 v40, 0xffff0000, v14
	v_lshlrev_b32_e32 v43, 16, v11
	v_lshlrev_b32_e32 v42, 16, v15
	v_and_b32_e32 v11, 0xffff0000, v11
	v_and_b32_e32 v10, 0xffff0000, v15
	v_lshlrev_b32_e32 v15, 16, v12
	v_lshlrev_b32_e32 v14, 16, v16
	v_and_b32_e32 v45, 0xffff0000, v12
	v_and_b32_e32 v44, 0xffff0000, v16
	v_lshlrev_b32_e32 v47, 16, v13
	v_lshlrev_b32_e32 v46, 16, v17
	v_and_b32_e32 v13, 0xffff0000, v13
	v_and_b32_e32 v12, 0xffff0000, v17
	s_waitcnt vmcnt(3)
	v_pk_mul_f32 v[16:17], v[22:23], v[38:39] op_sel:[0,1] op_sel_hi:[1,0]
	v_pk_mul_f32 v[22:23], v[22:23], v[38:39]
	v_pk_mul_f32 v[38:39], v[24:25], v[40:41] op_sel:[0,1] op_sel_hi:[1,0]
	v_pk_mul_f32 v[24:25], v[24:25], v[40:41]
	s_waitcnt vmcnt(2)
	v_pk_mul_f32 v[40:41], v[26:27], v[42:43] op_sel:[0,1] op_sel_hi:[1,0]
	v_pk_mul_f32 v[26:27], v[26:27], v[42:43]
	v_pk_mul_f32 v[42:43], v[28:29], v[10:11] op_sel:[0,1] op_sel_hi:[1,0]
	v_pk_mul_f32 v[10:11], v[28:29], v[10:11]
	s_waitcnt vmcnt(1)
	v_pk_mul_f32 v[28:29], v[30:31], v[14:15] op_sel:[0,1] op_sel_hi:[1,0]
	v_pk_mul_f32 v[14:15], v[30:31], v[14:15]
	v_pk_mul_f32 v[30:31], v[32:33], v[44:45] op_sel:[0,1] op_sel_hi:[1,0]
	v_pk_mul_f32 v[32:33], v[32:33], v[44:45]
	s_waitcnt vmcnt(0)
	v_pk_mul_f32 v[44:45], v[34:35], v[46:47] op_sel:[0,1] op_sel_hi:[1,0]
	v_pk_mul_f32 v[34:35], v[34:35], v[46:47]
	v_pk_mul_f32 v[46:47], v[36:37], v[12:13] op_sel:[0,1] op_sel_hi:[1,0]
	v_pk_mul_f32 v[12:13], v[36:37], v[12:13]
	v_sub_f32_e32 v0, v16, v17
	v_add_f32_e32 v16, v22, v23
	v_sub_f32_e32 v17, v38, v39
	v_add_f32_e32 v22, v24, v25
	v_sub_f32_e32 v23, v40, v41
	v_add_f32_e32 v24, v26, v27
	v_sub_f32_e32 v25, v42, v43
	v_add_f32_e32 v10, v10, v11
	v_sub_f32_e32 v11, v28, v29
	v_add_f32_e32 v14, v14, v15
	v_sub_f32_e32 v15, v30, v31
	v_add_f32_e32 v26, v32, v33
	v_sub_f32_e32 v27, v44, v45
	v_add_f32_e32 v28, v34, v35
	v_sub_f32_e32 v29, v46, v47
	v_add_f32_e32 v12, v12, v13
	v_mul_f32_e32 v13, 0x3e0293ee, v16
	v_mul_f32_e32 v16, 0x3e0293ee, v17
	v_mul_f32_e32 v17, 0x3e0293ee, v22
	v_mul_f32_e32 v22, 0x3e0293ee, v23
	v_mul_f32_e32 v23, 0x3e0293ee, v24
	v_mul_f32_e32 v24, 0x3e0293ee, v25
	v_mul_f32_e32 v10, 0x3e0293ee, v10
	v_mul_f32_e32 v11, 0x3e0293ee, v11
	v_mul_f32_e32 v14, 0x3e0293ee, v14
	v_mul_f32_e32 v15, 0x3e0293ee, v15
	v_mul_f32_e32 v25, 0x3e0293ee, v26
	v_mul_f32_e32 v26, 0x3e0293ee, v27
	v_mul_f32_e32 v27, 0x3e0293ee, v28
	v_mul_f32_e32 v28, 0x3e0293ee, v29
	v_mul_f32_e32 v12, 0x3e0293ee, v12
	v_mul_f32_e32 v0, 0x3e0293ee, v0
	v_cvt_pk_bf16_f32 v128, v0, v16
	v_cvt_pk_bf16_f32 v129, v22, v24
	v_cvt_pk_bf16_f32 v130, v11, v15
	v_cvt_pk_bf16_f32 v131, v26, v28
	v_cvt_pk_bf16_f32 v132, v13, v17
	v_cvt_pk_bf16_f32 v133, v23, v10
	v_cvt_pk_bf16_f32 v134, v14, v25
	v_cvt_pk_bf16_f32 v135, v27, v12
	s_waitcnt vmcnt(0)
	v_mov_b32_e32 v10, v188
	v_mov_b32_e32 v11, v189
	v_mov_b32_e32 v12, v190
	v_mov_b32_e32 v13, v191
	v_mov_b32_e32 v14, v192
	v_mov_b32_e32 v15, v193
	v_mov_b32_e32 v16, v194
	v_mov_b32_e32 v17, v195
	v_mov_b32_e32 v22, v206
	v_mov_b32_e32 v23, v207
	v_mov_b32_e32 v24, v208
	v_mov_b32_e32 v25, v209
	v_mov_b32_e32 v26, v210
	v_mov_b32_e32 v27, v211
	v_mov_b32_e32 v28, v212
	v_mov_b32_e32 v29, v213
	v_lshlrev_b32_e32 v21, 16, v2
	v_lshlrev_b32_e32 v20, 16, v6
	v_and_b32_e32 v31, 0xffff0000, v2
	v_and_b32_e32 v30, 0xffff0000, v6
	v_lshlrev_b32_e32 v33, 16, v3
	v_lshlrev_b32_e32 v32, 16, v7
	v_and_b32_e32 v3, 0xffff0000, v3
	v_and_b32_e32 v2, 0xffff0000, v7
	v_lshlrev_b32_e32 v7, 16, v4
	v_lshlrev_b32_e32 v6, 16, v8
	v_and_b32_e32 v35, 0xffff0000, v4
	v_and_b32_e32 v34, 0xffff0000, v8
	v_lshlrev_b32_e32 v37, 16, v5
	v_lshlrev_b32_e32 v36, 16, v9
	v_and_b32_e32 v5, 0xffff0000, v5
	v_and_b32_e32 v4, 0xffff0000, v9
	v_mov_b32_e32 v38, v198
	s_waitcnt vmcnt(3)
	v_pk_mul_f32 v[8:9], v[10:11], v[20:21] op_sel:[0,1] op_sel_hi:[1,0]
	v_pk_mul_f32 v[10:11], v[10:11], v[20:21]
	v_pk_mul_f32 v[20:21], v[12:13], v[30:31] op_sel:[0,1] op_sel_hi:[1,0]
	v_pk_mul_f32 v[12:13], v[12:13], v[30:31]
	s_waitcnt vmcnt(2)
	v_pk_mul_f32 v[30:31], v[14:15], v[32:33] op_sel:[0,1] op_sel_hi:[1,0]
	v_pk_mul_f32 v[14:15], v[14:15], v[32:33]
	v_pk_mul_f32 v[32:33], v[16:17], v[2:3] op_sel:[0,1] op_sel_hi:[1,0]
	v_pk_mul_f32 v[2:3], v[16:17], v[2:3]
	s_waitcnt vmcnt(1)
	v_pk_mul_f32 v[16:17], v[22:23], v[6:7] op_sel:[0,1] op_sel_hi:[1,0]
	v_pk_mul_f32 v[6:7], v[22:23], v[6:7]
	v_pk_mul_f32 v[22:23], v[24:25], v[34:35] op_sel:[0,1] op_sel_hi:[1,0]
	v_pk_mul_f32 v[24:25], v[24:25], v[34:35]
	s_waitcnt vmcnt(0)
	v_pk_mul_f32 v[34:35], v[26:27], v[36:37] op_sel:[0,1] op_sel_hi:[1,0]
	v_pk_mul_f32 v[26:27], v[26:27], v[36:37]
	v_pk_mul_f32 v[36:37], v[28:29], v[4:5] op_sel:[0,1] op_sel_hi:[1,0]
	v_pk_mul_f32 v[4:5], v[28:29], v[4:5]
	v_sub_f32_e32 v0, v8, v9
	v_add_f32_e32 v8, v10, v11
	v_sub_f32_e32 v9, v20, v21
	v_add_f32_e32 v10, v12, v13
	v_sub_f32_e32 v11, v30, v31
	v_add_f32_e32 v12, v14, v15
	v_sub_f32_e32 v13, v32, v33
	v_add_f32_e32 v2, v2, v3
	v_sub_f32_e32 v3, v16, v17
	v_add_f32_e32 v6, v6, v7
	v_sub_f32_e32 v7, v22, v23
	v_add_f32_e32 v14, v24, v25
	v_sub_f32_e32 v15, v34, v35
	v_add_f32_e32 v16, v26, v27
	v_sub_f32_e32 v17, v36, v37
	v_add_f32_e32 v4, v4, v5
	v_mul_f32_e32 v0, 0x3e0293ee, v0
	v_mul_f32_e32 v5, 0x3e0293ee, v8
	v_mul_f32_e32 v8, 0x3e0293ee, v9
	v_mul_f32_e32 v9, 0x3e0293ee, v10
	v_mul_f32_e32 v10, 0x3e0293ee, v11
	v_mul_f32_e32 v11, 0x3e0293ee, v12
	v_mul_f32_e32 v12, 0x3e0293ee, v13
	v_mul_f32_e32 v2, 0x3e0293ee, v2
	v_mul_f32_e32 v3, 0x3e0293ee, v3
	v_mul_f32_e32 v6, 0x3e0293ee, v6
	v_mul_f32_e32 v7, 0x3e0293ee, v7
	v_mul_f32_e32 v13, 0x3e0293ee, v14
	v_mul_f32_e32 v14, 0x3e0293ee, v15
	v_mul_f32_e32 v15, 0x3e0293ee, v16
	v_mul_f32_e32 v16, 0x3e0293ee, v17
	v_mul_f32_e32 v4, 0x3e0293ee, v4
	v_cvt_pk_bf16_f32 v136, v0, v8
	v_cvt_pk_bf16_f32 v137, v10, v12
	v_cvt_pk_bf16_f32 v138, v3, v7
	v_cvt_pk_bf16_f32 v139, v14, v16
	v_cvt_pk_bf16_f32 v140, v5, v9
	v_cvt_pk_bf16_f32 v141, v11, v2
	v_cvt_pk_bf16_f32 v142, v6, v13
	v_cvt_pk_bf16_f32 v143, v15, v4
	global_load_dwordx4 v[144:147], v[18:19], off
	v_readfirstlane_b32 s0, v38
	v_bfe_u32 v8, v38, 4, 2
	s_ashr_i32 s20, s0, 6
	v_bfe_u32 v0, v38, 2, 3
	v_lshrrev_b32_e32 v3, 1, v38
	v_bitop3_b32 v6, v8, v38, 15 bitop3:0x78
	s_lshl_b32 s0, s20, 3
	s_lshl_b32 s1, s20, 2
	v_and_b32_e32 v3, 8, v3
	v_lshlrev_b32_e32 v9, 3, v6
	v_bitop3_b32 v0, s0, v215, v0 bitop3:0xc8
	s_and_b32 s1, s1, 4
	v_or_b32_e32 v6, s0, v8
	v_or3_b32 v0, v3, v0, s1
	v_mul_lo_u32 v3, v6, s21
	v_mul_u32_u24_e32 v6, 0x1a00, v0
	v_or_b32_e32 v0, v3, v9
	v_or_b32_e32 v3, 4, v8
	v_and_b32_e32 v2, 15, v38
	v_lshlrev_b32_e32 v5, 3, v38
	v_or_b32_e32 v3, s0, v3
	s_lshl_b32 s0, s20, 11
	s_add_i32 s1, 0, 0x10000
	v_and_b32_e32 v4, 32, v38
	v_and_b32_e32 v5, 24, v5
	v_bitop3_b32 v2, v8, v2, 4 bitop3:0x36
	s_add_i32 s35, s1, s0
	v_lshlrev_b32_e32 v10, 3, v2
	v_mul_lo_u32 v2, v3, s21
	v_or3_b32 v158, v4, v5, v6
	v_lshl_add_u64 v[6:7], v[0:1], 1, s[4:5]
	s_mov_b32 m0, s35
	s_add_i32 s36, s0, 0
	v_or_b32_e32 v2, v2, v10
	global_load_lds_dwordx4 v[6:7], off
	v_lshl_add_u64 v[6:7], v[158:159], 1, s[6:7]
	s_mov_b32 m0, s36
	v_mov_b32_e32 v3, v1
	s_or_b32 s14, s0, 0x400
	v_or_b32_e32 v4, 64, v158
	global_load_lds_dwordx4 v[6:7], off
	v_lshl_add_u64 v[6:7], v[2:3], 1, s[4:5]
	s_add_i32 m0, s1, s14
	v_mov_b32_e32 v5, v1
	global_load_lds_dwordx4 v[6:7], off
	v_lshl_add_u64 v[4:5], v[4:5], 1, s[6:7]
	s_add_i32 m0, s36, 0x400
	v_add_u32_e32 v0, 0x68000, v0
	s_add_i32 s1, 0, 0x14000
	global_load_lds_dwordx4 v[4:5], off
	v_lshl_add_u64 v[4:5], v[0:1], 1, s[4:5]
	s_add_i32 m0, s1, s0
	v_add_u32_e32 v0, 0x68000, v158
	global_load_lds_dwordx4 v[4:5], off
	v_lshl_add_u64 v[4:5], v[0:1], 1, s[6:7]
	s_add_i32 m0, s36, 0x4000
	v_add_u32_e32 v0, 0x68000, v2
	global_load_lds_dwordx4 v[4:5], off
	v_lshl_add_u64 v[2:3], v[0:1], 1, s[4:5]
	s_add_i32 m0, s1, s14
	v_add_u32_e32 v0, 0x68040, v158
	global_load_lds_dwordx4 v[2:3], off
	v_lshl_add_u64 v[2:3], v[0:1], 1, s[6:7]
	s_add_i32 m0, s36, 0x4400
	v_and_b32_e32 v4, 0x3fffffc0, v38
	global_load_lds_dwordx4 v[2:3], off
	v_readlane_b32 s0, v254, 1
	v_and_b32_e32 v2, 31, v38
	v_bfe_u32 v3, v38, 5, 1
	v_lshl_add_u32 v165, v4, 2, s0
	v_lshlrev_b32_e32 v166, 8, v2
	v_lshl_add_u32 v173, v2, 2, v165
	v_add_u32_e32 v2, s18, v164
	v_add_u32_e32 v159, s18, v163
	v_and_b32_e32 v0, 63, v38
	v_lshlrev_b32_e32 v5, 4, v38
	v_lshlrev_b32_e32 v167, 4, v3
	v_lshlrev_b32_e32 v174, 2, v3
	v_ashrrev_i32_e32 v3, 31, v2
	v_readlane_b32 s18, v253, 59
	v_lshlrev_b32_e32 v4, 3, v0
	v_and_b32_e32 v6, 0xc0, v5
	v_lshlrev_b32_e32 v7, 1, v38
	s_cmp_gt_i32 s20, 3
	v_lshlrev_b64 v[2:3], 8, v[2:3]
	v_readlane_b32 s19, v253, 60
	v_and_or_b32 v6, v4, 24, v6
	v_and_b32_e32 v7, 32, v7
	v_and_b32_e32 v4, 0x100, v4
	s_movk_i32 s0, 0x70
	s_cselect_b64 s[14:15], -1, 0
	s_cmp_lt_i32 s20, 4
	v_lshl_add_u64 v[160:161], s[18:19], 0, v[2:3]
	s_mul_i32 s18, s20, 0xd000
	v_or3_b32 v4, v6, v7, v4
	v_and_b32_e32 v6, 0x70, v5
	v_bitop3_b32 v168, v167, v5, s0 bitop3:0x78
	s_movk_i32 s0, 0x60
	s_cselect_b64 s[16:17], -1, 0
	s_add_i32 s19, s18, 0xd6800
	v_bitop3_b32 v171, v167, v6, s0 bitop3:0x36
	v_cmp_gt_u32_e64 s[0:1], 32, v0
	v_mov_b32_e32 v0, s19
	v_mad_u32_u24 v0, v8, s21, v0
	s_add_i32 s18, s18, 0xd0000
	v_or_b32_e32 v175, v0, v10
	v_mov_b32_e32 v0, s18
	s_waitcnt vmcnt(4)
	v_mad_u32_u24 v0, v8, s21, v0
	v_mov_b32_e32 v14, v1
	v_mov_b32_e32 v15, v1
	v_bitop3_b32 v169, v167, v6, 32 bitop3:0x36
	v_bitop3_b32 v170, v167, v6, 64 bitop3:0x36
	v_add_u32_e32 v172, 0, v4
	v_or_b32_e32 v176, v0, v9
	v_mov_b32_e32 v0, v1
	v_mov_b32_e32 v2, v1
	v_mov_b32_e32 v3, v1
	v_mov_b32_e32 v4, v1
	v_mov_b32_e32 v5, v1
	v_mov_b32_e32 v6, v1
	v_mov_b32_e32 v7, v1
	v_mov_b32_e32 v8, v1
	v_mov_b32_e32 v9, v1
	v_mov_b32_e32 v10, v1
	v_mov_b32_e32 v11, v1
	v_mov_b32_e32 v12, v1
	v_mov_b32_e32 v13, v1
	v_mov_b64_e32 v[30:31], v[14:15]
	v_mov_b64_e32 v[46:47], v[14:15]
	v_mov_b64_e32 v[62:63], v[14:15]
	v_mov_b64_e32 v[78:79], v[14:15]
	v_mov_b64_e32 v[94:95], v[14:15]
	v_mov_b64_e32 v[110:111], v[14:15]
	s_add_i32 s38, s38, 0x208000
	s_mov_b64 s[20:21], 0
	v_mov_b64_e32 v[28:29], v[12:13]
	v_mov_b64_e32 v[26:27], v[10:11]
	v_mov_b64_e32 v[24:25], v[8:9]
	v_mov_b64_e32 v[22:23], v[6:7]
	v_mov_b64_e32 v[20:21], v[4:5]
	v_mov_b64_e32 v[18:19], v[2:3]
	v_mov_b64_e32 v[16:17], v[0:1]
	v_mov_b64_e32 v[44:45], v[12:13]
	v_mov_b64_e32 v[42:43], v[10:11]
	v_mov_b64_e32 v[40:41], v[8:9]
	v_mov_b64_e32 v[38:39], v[6:7]
	v_mov_b64_e32 v[36:37], v[4:5]
	v_mov_b64_e32 v[34:35], v[2:3]
	v_mov_b64_e32 v[32:33], v[0:1]
	v_mov_b64_e32 v[60:61], v[12:13]
	v_mov_b64_e32 v[58:59], v[10:11]
	v_mov_b64_e32 v[56:57], v[8:9]
	v_mov_b64_e32 v[54:55], v[6:7]
	v_mov_b64_e32 v[52:53], v[4:5]
	v_mov_b64_e32 v[50:51], v[2:3]
	v_mov_b64_e32 v[48:49], v[0:1]
	v_mov_b64_e32 v[76:77], v[12:13]
	v_mov_b64_e32 v[74:75], v[10:11]
	v_mov_b64_e32 v[72:73], v[8:9]
	v_mov_b64_e32 v[70:71], v[6:7]
	v_mov_b64_e32 v[68:69], v[4:5]
	v_mov_b64_e32 v[66:67], v[2:3]
	v_mov_b64_e32 v[64:65], v[0:1]
	v_mov_b64_e32 v[92:93], v[12:13]
	v_mov_b64_e32 v[90:91], v[10:11]
	v_mov_b64_e32 v[88:89], v[8:9]
	v_mov_b64_e32 v[86:87], v[6:7]
	v_mov_b64_e32 v[84:85], v[4:5]
	v_mov_b64_e32 v[82:83], v[2:3]
	v_mov_b64_e32 v[80:81], v[0:1]
	v_mov_b64_e32 v[108:109], v[12:13]
	v_mov_b64_e32 v[106:107], v[10:11]
	v_mov_b64_e32 v[104:105], v[8:9]
	v_mov_b64_e32 v[102:103], v[6:7]
	v_mov_b64_e32 v[100:101], v[4:5]
	v_mov_b64_e32 v[98:99], v[2:3]
	v_mov_b64_e32 v[96:97], v[0:1]
	s_waitcnt vmcnt(4) lgkmcnt(0)
	s_barrier

.LBB0_1249:
	v_mov_b32_e32 v0, v198
	s_add_i32 s2, s0, s10
	s_mov_b32 s0, 0x1fffffe0
	v_lshrrev_b32_e32 v66, 1, v0
	v_and_b32_e32 v67, 31, v0
	v_and_or_b32 v66, v66, s0, v67
	v_readlane_b32 s0, v252, 26
	v_readlane_b32 s1, v252, 27
	v_lshl_add_u32 v66, v66, 3, s31
	v_lshrrev_b32_e32 v0, 2, v0
	v_mov_b64_e32 v[68:69], s[0:1]
	s_movk_i32 s0, 0x4400
	v_mad_i64_i32 v[68:69], s[0:1], v66, s0, v[68:69]
	s_lshl_b32 s2, s2, 8
	v_and_b32_e32 v72, 8, v0
	v_lshl_add_u64 v[68:69], v[68:69], 0, s[2:3]
	v_lshlrev_b32_e32 v0, 1, v72
	v_lshl_add_u64 v[70:71], v[68:69], 0, v[0:1]
	global_load_dwordx4 v[84:87], v[70:71], off
	global_load_dwordx4 v[88:91], v[70:71], off offset:128
	v_ashrrev_i32_e32 v67, 31, v66
	v_readlane_b32 s0, v251, 5
	v_lshlrev_b64 v[66:67], 9, v[66:67]
	v_readlane_b32 s1, v251, 6
	v_lshlrev_b32_e32 v0, 3, v72
	s_add_u32 s16, s11, s2
	v_lshl_add_u64 v[66:67], s[0:1], 0, v[66:67]
	v_lshl_add_u64 v[82:83], v[66:67], 0, v[0:1]
	global_load_dwordx4 v[130:133], v[82:83], off offset:128
	global_load_dwordx4 v[134:137], v[82:83], off offset:144
	global_load_dwordx4 v[138:141], v[82:83], off offset:160
	global_load_dwordx4 v[142:145], v[82:83], off offset:176
	global_load_dwordx4 v[206:209], v[82:83], off offset:256
	global_load_dwordx4 v[210:213], v[82:83], off offset:272
	global_load_dwordx4 v[216:219], v[82:83], off offset:288
	global_load_dwordx4 v[224:227], v[82:83], off offset:304
	global_load_dwordx4 v[228:231], v[82:83], off offset:384
	global_load_dwordx4 v[232:235], v[82:83], off offset:400
	global_load_dwordx4 v[236:239], v[82:83], off offset:416
	global_load_dwordx4 v[240:243], v[82:83], off offset:432
	global_load_dwordx4 v[92:95], v[82:83], off
	global_load_dwordx4 v[96:99], v[82:83], off offset:16
	global_load_dwordx4 v[100:103], v[82:83], off offset:32
	global_load_dwordx4 v[104:107], v[82:83], off offset:48
	global_load_dwordx4 v[108:111], v[70:71], off offset:32
	global_load_dwordx4 v[74:77], v[70:71], off offset:64
	global_load_dwordx4 v[66:69], v[70:71], off offset:96
	global_load_dwordx4 v[112:115], v[70:71], off offset:160
	global_load_dwordx4 v[78:81], v[70:71], off offset:192
	s_nop 0
	global_load_dwordx4 v[70:73], v[70:71], off offset:224
	s_addc_u32 s17, s35, 0
	s_and_b64 s[0:1], s[12:13], exec
	s_movk_i32 s0, 0x80
	s_cselect_b32 s2, s0, 0x100
	s_movk_i32 s0, 0x800
	s_cselect_b32 s37, s36, s34
	s_cselect_b32 s38, 8, 4
	s_cselect_b32 s39, 0x200, s0
	s_cselect_b32 s40, 0, 15
	s_add_u32 s18, s16, 0x1200
	s_addc_u32 s19, s17, 0
	v_mov_b32_e32 v189, v1
	v_mov_b32_e32 v191, v1
	v_subrev_u32_e32 v223, s37, v195
	s_mov_b32 s45, 0
	s_mov_b32 s49, 0
	s_mov_b32 s50, 0
	s_mov_b32 s51, 0
	s_mov_b32 s52, 0
	s_waitcnt vmcnt(11)
	v_lshlrev_b32_e32 v117, 16, v84
	s_waitcnt vmcnt(10)
	v_lshlrev_b32_e32 v116, 16, v88
	v_and_b32_e32 v119, 0xffff0000, v84
	v_and_b32_e32 v118, 0xffff0000, v88
	v_lshlrev_b32_e32 v121, 16, v85
	v_lshlrev_b32_e32 v120, 16, v89
	v_and_b32_e32 v85, 0xffff0000, v85
	v_and_b32_e32 v84, 0xffff0000, v89
	v_lshlrev_b32_e32 v89, 16, v86
	v_lshlrev_b32_e32 v88, 16, v90
	v_and_b32_e32 v123, 0xffff0000, v86
	v_and_b32_e32 v122, 0xffff0000, v90
	v_lshlrev_b32_e32 v125, 16, v87
	v_lshlrev_b32_e32 v124, 16, v91
	v_and_b32_e32 v87, 0xffff0000, v87
	v_and_b32_e32 v86, 0xffff0000, v91
	s_waitcnt vmcnt(9)
	v_pk_mul_f32 v[90:91], v[92:93], v[116:117] op_sel:[0,1] op_sel_hi:[1,0]
	v_pk_mul_f32 v[92:93], v[92:93], v[116:117]
	v_pk_mul_f32 v[116:117], v[94:95], v[118:119] op_sel:[0,1] op_sel_hi:[1,0]
	v_pk_mul_f32 v[94:95], v[94:95], v[118:119]
	s_waitcnt vmcnt(8)
	v_pk_mul_f32 v[118:119], v[96:97], v[120:121] op_sel:[0,1] op_sel_hi:[1,0]
	v_pk_mul_f32 v[96:97], v[96:97], v[120:121]
	v_pk_mul_f32 v[120:121], v[98:99], v[84:85] op_sel:[0,1] op_sel_hi:[1,0]
	v_pk_mul_f32 v[84:85], v[98:99], v[84:85]
	s_waitcnt vmcnt(7)
	v_pk_mul_f32 v[98:99], v[100:101], v[88:89] op_sel:[0,1] op_sel_hi:[1,0]
	v_pk_mul_f32 v[88:89], v[100:101], v[88:89]
	v_pk_mul_f32 v[100:101], v[102:103], v[122:123] op_sel:[0,1] op_sel_hi:[1,0]
	v_pk_mul_f32 v[102:103], v[102:103], v[122:123]
	s_waitcnt vmcnt(6)
	v_pk_mul_f32 v[122:123], v[104:105], v[124:125] op_sel:[0,1] op_sel_hi:[1,0]
	v_pk_mul_f32 v[104:105], v[104:105], v[124:125]
	v_pk_mul_f32 v[124:125], v[106:107], v[86:87] op_sel:[0,1] op_sel_hi:[1,0]
	v_add_f32_e32 v84, v84, v85
	v_sub_f32_e32 v0, v90, v91
	v_add_f32_e32 v90, v92, v93
	v_add_f32_e32 v92, v94, v95
	v_add_f32_e32 v94, v96, v97
	v_sub_f32_e32 v85, v98, v99
	v_add_f32_e32 v96, v102, v103
	v_mul_f32_e32 v103, 0x3e0293ee, v84
	v_sub_f32_e32 v84, v124, v125
	v_add_f32_e32 v88, v88, v89
	v_sub_f32_e32 v89, v100, v101
	v_mul_f32_e32 v100, 0x3e0293ee, v85
	v_mul_f32_e32 v101, 0x3e0293ee, v84
	v_pk_mul_f32 v[84:85], v[106:107], v[86:87]
	v_sub_f32_e32 v91, v116, v117
	v_sub_f32_e32 v93, v118, v119
	v_sub_f32_e32 v95, v120, v121
	v_add_f32_e32 v98, v104, v105
	v_add_f32_e32 v84, v84, v85
	v_sub_f32_e32 v97, v122, v123
	v_mul_f32_e32 v90, 0x3e0293ee, v90
	v_mul_f32_e32 v91, 0x3e0293ee, v91
	v_mul_f32_e32 v92, 0x3e0293ee, v92
	v_mul_f32_e32 v93, 0x3e0293ee, v93
	v_mul_f32_e32 v94, 0x3e0293ee, v94
	v_mul_f32_e32 v95, 0x3e0293ee, v95
	v_mul_f32_e32 v88, 0x3e0293ee, v88
	v_mul_f32_e32 v89, 0x3e0293ee, v89
	v_mul_f32_e32 v105, 0x3e0293ee, v98
	v_mul_f32_e32 v84, 0x3e0293ee, v84
	v_mul_f32_e32 v0, 0x3e0293ee, v0
	v_mul_f32_e32 v96, 0x3e0293ee, v96
	v_mul_f32_e32 v97, 0x3e0293ee, v97
	v_cvt_pk_bf16_f32 v98, v0, v91
	v_cvt_pk_bf16_f32 v99, v93, v95
	v_cvt_pk_bf16_f32 v100, v100, v89
	v_cvt_pk_bf16_f32 v101, v97, v101
	v_cvt_pk_bf16_f32 v102, v90, v92
	v_cvt_pk_bf16_f32 v103, v94, v103
	v_cvt_pk_bf16_f32 v104, v88, v96
	v_cvt_pk_bf16_f32 v105, v105, v84
	s_waitcnt vmcnt(0)
	v_mov_b32_e32 v84, v130
	v_mov_b32_e32 v85, v131
	v_mov_b32_e32 v86, v132
	v_mov_b32_e32 v87, v133
	v_mov_b32_e32 v88, v134
	v_mov_b32_e32 v89, v135
	v_mov_b32_e32 v90, v136
	v_mov_b32_e32 v91, v137
	v_mov_b32_e32 v92, v138
	v_mov_b32_e32 v93, v139
	v_mov_b32_e32 v94, v140
	v_mov_b32_e32 v95, v141
	v_mov_b32_e32 v116, v142
	v_mov_b32_e32 v117, v143
	v_mov_b32_e32 v118, v144
	v_mov_b32_e32 v119, v145
	s_waitcnt vmcnt(9)
	v_lshlrev_b32_e32 v97, 16, v108
	s_waitcnt vmcnt(6)
	v_lshlrev_b32_e32 v96, 16, v112
	v_and_b32_e32 v107, 0xffff0000, v108
	v_and_b32_e32 v106, 0xffff0000, v112
	v_lshlrev_b32_e32 v121, 16, v109
	v_lshlrev_b32_e32 v120, 16, v113
	v_and_b32_e32 v109, 0xffff0000, v109
	v_and_b32_e32 v108, 0xffff0000, v113
	v_lshlrev_b32_e32 v113, 16, v110
	v_lshlrev_b32_e32 v112, 16, v114
	v_and_b32_e32 v123, 0xffff0000, v110
	v_and_b32_e32 v122, 0xffff0000, v114
	v_lshlrev_b32_e32 v125, 16, v111
	v_lshlrev_b32_e32 v124, 16, v115
	v_and_b32_e32 v111, 0xffff0000, v111
	v_and_b32_e32 v110, 0xffff0000, v115
	s_waitcnt vmcnt(3)
	v_pk_mul_f32 v[114:115], v[84:85], v[96:97] op_sel:[0,1] op_sel_hi:[1,0]
	v_pk_mul_f32 v[84:85], v[84:85], v[96:97]
	v_pk_mul_f32 v[96:97], v[86:87], v[106:107] op_sel:[0,1] op_sel_hi:[1,0]
	v_pk_mul_f32 v[86:87], v[86:87], v[106:107]
	s_waitcnt vmcnt(2)
	v_pk_mul_f32 v[106:107], v[88:89], v[120:121] op_sel:[0,1] op_sel_hi:[1,0]
	v_pk_mul_f32 v[88:89], v[88:89], v[120:121]
	v_pk_mul_f32 v[120:121], v[90:91], v[108:109] op_sel:[0,1] op_sel_hi:[1,0]
	v_pk_mul_f32 v[90:91], v[90:91], v[108:109]
	s_waitcnt vmcnt(1)
	v_pk_mul_f32 v[108:109], v[92:93], v[112:113] op_sel:[0,1] op_sel_hi:[1,0]
	v_pk_mul_f32 v[92:93], v[92:93], v[112:113]
	v_pk_mul_f32 v[112:113], v[94:95], v[122:123] op_sel:[0,1] op_sel_hi:[1,0]
	v_pk_mul_f32 v[94:95], v[94:95], v[122:123]
	s_waitcnt vmcnt(0)
	v_pk_mul_f32 v[122:123], v[116:117], v[124:125] op_sel:[0,1] op_sel_hi:[1,0]
	v_pk_mul_f32 v[116:117], v[116:117], v[124:125]
	v_pk_mul_f32 v[124:125], v[118:119], v[110:111] op_sel:[0,1] op_sel_hi:[1,0]
	v_pk_mul_f32 v[110:111], v[118:119], v[110:111]
	v_add_f32_e32 v84, v84, v85
	v_sub_f32_e32 v85, v96, v97
	v_add_f32_e32 v86, v86, v87
	v_sub_f32_e32 v87, v106, v107
	v_add_f32_e32 v88, v88, v89
	v_sub_f32_e32 v89, v120, v121
	v_add_f32_e32 v90, v90, v91
	v_sub_f32_e32 v91, v108, v109
	v_add_f32_e32 v92, v92, v93
	v_sub_f32_e32 v93, v112, v113
	v_add_f32_e32 v94, v94, v95
	v_sub_f32_e32 v95, v122, v123
	v_add_f32_e32 v106, v110, v111
	v_sub_f32_e32 v0, v114, v115
	v_add_f32_e32 v96, v116, v117
	v_sub_f32_e32 v97, v124, v125
	v_mul_f32_e32 v84, 0x3e0293ee, v84
	v_mul_f32_e32 v85, 0x3e0293ee, v85
	v_mul_f32_e32 v86, 0x3e0293ee, v86
	v_mul_f32_e32 v87, 0x3e0293ee, v87
	v_mul_f32_e32 v88, 0x3e0293ee, v88
	v_mul_f32_e32 v89, 0x3e0293ee, v89
	v_mul_f32_e32 v90, 0x3e0293ee, v90
	v_mul_f32_e32 v91, 0x3e0293ee, v91
	v_mul_f32_e32 v92, 0x3e0293ee, v92
	v_mul_f32_e32 v93, 0x3e0293ee, v93
	v_mul_f32_e32 v94, 0x3e0293ee, v94
	v_mul_f32_e32 v95, 0x3e0293ee, v95
	v_mul_f32_e32 v113, 0x3e0293ee, v106
	v_mul_f32_e32 v0, 0x3e0293ee, v0
	v_mul_f32_e32 v96, 0x3e0293ee, v96
	v_mul_f32_e32 v97, 0x3e0293ee, v97
	v_cvt_pk_bf16_f32 v106, v0, v85
	v_cvt_pk_bf16_f32 v107, v87, v89
	v_cvt_pk_bf16_f32 v108, v91, v93
	v_cvt_pk_bf16_f32 v109, v95, v97
	v_cvt_pk_bf16_f32 v110, v84, v86
	v_cvt_pk_bf16_f32 v111, v88, v90
	v_cvt_pk_bf16_f32 v112, v92, v94
	v_cvt_pk_bf16_f32 v113, v96, v113
	s_waitcnt vmcnt(0)
	v_mov_b32_e32 v84, v206
	v_mov_b32_e32 v85, v207
	v_mov_b32_e32 v86, v208
	v_mov_b32_e32 v87, v209
	v_mov_b32_e32 v88, v210
	v_mov_b32_e32 v89, v211
	v_mov_b32_e32 v90, v212
	v_mov_b32_e32 v91, v213
	v_mov_b32_e32 v92, v216
	v_mov_b32_e32 v93, v217
	v_mov_b32_e32 v94, v218
	v_mov_b32_e32 v95, v219
	v_mov_b32_e32 v114, v224
	v_mov_b32_e32 v115, v225
	v_mov_b32_e32 v116, v226
	v_mov_b32_e32 v117, v227
	v_lshlrev_b32_e32 v97, 16, v74
	v_lshlrev_b32_e32 v96, 16, v78
	v_and_b32_e32 v119, 0xffff0000, v74
	v_and_b32_e32 v118, 0xffff0000, v78
	v_lshlrev_b32_e32 v121, 16, v75
	v_lshlrev_b32_e32 v120, 16, v79
	v_and_b32_e32 v75, 0xffff0000, v75
	v_and_b32_e32 v74, 0xffff0000, v79
	v_lshlrev_b32_e32 v79, 16, v76
	v_lshlrev_b32_e32 v78, 16, v80
	v_and_b32_e32 v123, 0xffff0000, v76
	v_and_b32_e32 v122, 0xffff0000, v80
	v_lshlrev_b32_e32 v125, 16, v77
	v_lshlrev_b32_e32 v124, 16, v81
	v_and_b32_e32 v77, 0xffff0000, v77
	v_and_b32_e32 v76, 0xffff0000, v81
	s_waitcnt vmcnt(3)
	v_pk_mul_f32 v[80:81], v[84:85], v[96:97] op_sel:[0,1] op_sel_hi:[1,0]
	v_pk_mul_f32 v[84:85], v[84:85], v[96:97]
	v_pk_mul_f32 v[96:97], v[86:87], v[118:119] op_sel:[0,1] op_sel_hi:[1,0]
	v_pk_mul_f32 v[86:87], v[86:87], v[118:119]
	s_waitcnt vmcnt(2)
	v_pk_mul_f32 v[118:119], v[88:89], v[120:121] op_sel:[0,1] op_sel_hi:[1,0]
	v_pk_mul_f32 v[88:89], v[88:89], v[120:121]
	v_pk_mul_f32 v[120:121], v[90:91], v[74:75] op_sel:[0,1] op_sel_hi:[1,0]
	v_pk_mul_f32 v[74:75], v[90:91], v[74:75]
	s_waitcnt vmcnt(1)
	v_pk_mul_f32 v[90:91], v[92:93], v[78:79] op_sel:[0,1] op_sel_hi:[1,0]
	v_pk_mul_f32 v[78:79], v[92:93], v[78:79]
	v_pk_mul_f32 v[92:93], v[94:95], v[122:123] op_sel:[0,1] op_sel_hi:[1,0]
	v_pk_mul_f32 v[94:95], v[94:95], v[122:123]
	s_waitcnt vmcnt(0)
	v_pk_mul_f32 v[122:123], v[114:115], v[124:125] op_sel:[0,1] op_sel_hi:[1,0]
	v_pk_mul_f32 v[114:115], v[114:115], v[124:125]
	v_pk_mul_f32 v[124:125], v[116:117], v[76:77] op_sel:[0,1] op_sel_hi:[1,0]
	v_pk_mul_f32 v[76:77], v[116:117], v[76:77]
	v_sub_f32_e32 v0, v80, v81
	v_add_f32_e32 v80, v84, v85
	v_sub_f32_e32 v81, v96, v97
	v_add_f32_e32 v84, v86, v87
	v_sub_f32_e32 v85, v118, v119
	v_add_f32_e32 v86, v88, v89
	v_sub_f32_e32 v87, v120, v121
	v_add_f32_e32 v74, v74, v75
	v_sub_f32_e32 v75, v90, v91
	v_add_f32_e32 v78, v78, v79
	v_sub_f32_e32 v79, v92, v93
	v_add_f32_e32 v88, v94, v95
	v_sub_f32_e32 v89, v122, v123
	v_add_f32_e32 v90, v114, v115
	v_sub_f32_e32 v91, v124, v125
	v_add_f32_e32 v76, v76, v77
	v_mul_f32_e32 v77, 0x3e0293ee, v80
	v_mul_f32_e32 v80, 0x3e0293ee, v81
	v_mul_f32_e32 v81, 0x3e0293ee, v84
	v_mul_f32_e32 v84, 0x3e0293ee, v85
	v_mul_f32_e32 v85, 0x3e0293ee, v86
	v_mul_f32_e32 v86, 0x3e0293ee, v87
	v_mul_f32_e32 v74, 0x3e0293ee, v74
	v_mul_f32_e32 v75, 0x3e0293ee, v75
	v_mul_f32_e32 v78, 0x3e0293ee, v78
	v_mul_f32_e32 v79, 0x3e0293ee, v79
	v_mul_f32_e32 v87, 0x3e0293ee, v88
	v_mul_f32_e32 v88, 0x3e0293ee, v89
	v_mul_f32_e32 v89, 0x3e0293ee, v90
	v_mul_f32_e32 v90, 0x3e0293ee, v91
	v_mul_f32_e32 v76, 0x3e0293ee, v76
	v_mul_f32_e32 v0, 0x3e0293ee, v0
	v_cvt_pk_bf16_f32 v114, v0, v80
	v_cvt_pk_bf16_f32 v115, v84, v86
	v_cvt_pk_bf16_f32 v116, v75, v79
	v_cvt_pk_bf16_f32 v117, v88, v90
	v_cvt_pk_bf16_f32 v118, v77, v81
	v_cvt_pk_bf16_f32 v119, v85, v74
	v_cvt_pk_bf16_f32 v120, v78, v87
	v_cvt_pk_bf16_f32 v121, v89, v76
	s_waitcnt vmcnt(0)
	v_mov_b32_e32 v74, v228
	v_mov_b32_e32 v75, v229
	v_mov_b32_e32 v76, v230
	v_mov_b32_e32 v77, v231
	v_mov_b32_e32 v78, v232
	v_mov_b32_e32 v79, v233
	v_mov_b32_e32 v80, v234
	v_mov_b32_e32 v81, v235
	v_mov_b32_e32 v84, v236
	v_mov_b32_e32 v85, v237
	v_mov_b32_e32 v86, v238
	v_mov_b32_e32 v87, v239
	v_mov_b32_e32 v88, v240
	v_mov_b32_e32 v89, v241
	v_mov_b32_e32 v90, v242
	v_mov_b32_e32 v91, v243
	v_lshlrev_b32_e32 v83, 16, v66
	v_lshlrev_b32_e32 v82, 16, v70
	v_and_b32_e32 v93, 0xffff0000, v66
	v_and_b32_e32 v92, 0xffff0000, v70
	v_lshlrev_b32_e32 v95, 16, v67
	v_lshlrev_b32_e32 v94, 16, v71
	v_and_b32_e32 v67, 0xffff0000, v67
	v_and_b32_e32 v66, 0xffff0000, v71
	v_lshlrev_b32_e32 v71, 16, v68
	v_lshlrev_b32_e32 v70, 16, v72
	v_and_b32_e32 v97, 0xffff0000, v68
	v_and_b32_e32 v96, 0xffff0000, v72
	v_lshlrev_b32_e32 v123, 16, v69
	v_lshlrev_b32_e32 v122, 16, v73
	v_and_b32_e32 v69, 0xffff0000, v69
	v_and_b32_e32 v68, 0xffff0000, v73
	s_waitcnt vmcnt(3)
	v_pk_mul_f32 v[72:73], v[74:75], v[82:83] op_sel:[0,1] op_sel_hi:[1,0]
	v_pk_mul_f32 v[74:75], v[74:75], v[82:83]
	v_pk_mul_f32 v[82:83], v[76:77], v[92:93] op_sel:[0,1] op_sel_hi:[1,0]
	v_pk_mul_f32 v[76:77], v[76:77], v[92:93]
	s_waitcnt vmcnt(2)
	v_pk_mul_f32 v[92:93], v[78:79], v[94:95] op_sel:[0,1] op_sel_hi:[1,0]
	v_pk_mul_f32 v[78:79], v[78:79], v[94:95]
	v_pk_mul_f32 v[94:95], v[80:81], v[66:67] op_sel:[0,1] op_sel_hi:[1,0]
	v_pk_mul_f32 v[66:67], v[80:81], v[66:67]
	s_waitcnt vmcnt(1)
	v_pk_mul_f32 v[80:81], v[84:85], v[70:71] op_sel:[0,1] op_sel_hi:[1,0]
	v_pk_mul_f32 v[70:71], v[84:85], v[70:71]
	v_pk_mul_f32 v[84:85], v[86:87], v[96:97] op_sel:[0,1] op_sel_hi:[1,0]
	v_pk_mul_f32 v[86:87], v[86:87], v[96:97]
	s_waitcnt vmcnt(0)
	v_pk_mul_f32 v[96:97], v[88:89], v[122:123] op_sel:[0,1] op_sel_hi:[1,0]
	v_pk_mul_f32 v[88:89], v[88:89], v[122:123]
	v_pk_mul_f32 v[122:123], v[90:91], v[68:69] op_sel:[0,1] op_sel_hi:[1,0]
	v_add_f32_e32 v70, v70, v71
	v_pk_mul_f32 v[68:69], v[90:91], v[68:69]
	v_sub_f32_e32 v0, v72, v73
	v_add_f32_e32 v72, v74, v75
	v_sub_f32_e32 v73, v82, v83
	v_add_f32_e32 v74, v76, v77
	v_sub_f32_e32 v75, v92, v93
	v_add_f32_e32 v76, v78, v79
	v_sub_f32_e32 v77, v94, v95
	v_add_f32_e32 v66, v66, v67
	v_sub_f32_e32 v67, v80, v81
	v_sub_f32_e32 v71, v84, v85
	v_add_f32_e32 v78, v86, v87
	v_sub_f32_e32 v79, v96, v97
	v_add_f32_e32 v80, v88, v89
	v_sub_f32_e32 v81, v122, v123
	v_mul_f32_e32 v70, 0x3e0293ee, v70
	v_add_f32_e32 v68, v68, v69
	v_mul_f32_e32 v0, 0x3e0293ee, v0
	v_mul_f32_e32 v69, 0x3e0293ee, v72
	v_mul_f32_e32 v72, 0x3e0293ee, v73
	v_mul_f32_e32 v73, 0x3e0293ee, v74
	v_mul_f32_e32 v74, 0x3e0293ee, v75
	v_mul_f32_e32 v75, 0x3e0293ee, v76
	v_mul_f32_e32 v76, 0x3e0293ee, v77
	v_mul_f32_e32 v66, 0x3e0293ee, v66
	v_mul_f32_e32 v67, 0x3e0293ee, v67
	v_mul_f32_e32 v71, 0x3e0293ee, v71
	v_mul_f32_e32 v77, 0x3e0293ee, v78
	v_mul_f32_e32 v78, 0x3e0293ee, v79
	v_mul_f32_e32 v79, 0x3e0293ee, v80
	v_mul_f32_e32 v80, 0x3e0293ee, v81
	v_cvt_pk_bf16_f32 v122, v0, v72
	v_cvt_pk_bf16_f32 v123, v74, v76
	v_cvt_pk_bf16_f32 v124, v67, v71
	v_cvt_pk_bf16_f32 v125, v78, v80
	v_cvt_pk_bf16_f32 v126, v69, v73
	v_cvt_pk_bf16_f32 v127, v75, v66
	v_cvt_pk_bf16_f32 v128, v70, v77
	v_mov_b32_e32 v70, v198
	v_mul_f32_e32 v68, 0x3e0293ee, v68
	v_cvt_pk_bf16_f32 v129, v79, v68
	v_mov_b32_e32 v80, v1
	v_readfirstlane_b32 s0, v70
	s_ashr_i32 s4, s0, 6
	s_lshl_b32 s5, s4, 3
	v_bfe_u32 v0, v70, 2, 3
	v_lshrrev_b32_e32 v68, 1, v70
	s_lshl_b32 s0, s4, 2
	v_bitop3_b32 v0, s5, v215, v0 bitop3:0xc8
	v_and_b32_e32 v68, 8, v68
	s_and_b32 s0, s0, 4
	v_or3_b32 v0, v68, v0, s0
	s_and_b64 s[0:1], s[12:13], exec
	s_cselect_b32 s41, 2, 3
	v_lshlrev_b32_e32 v0, s41, v0
	v_lshlrev_b32_e32 v69, 3, v70
	v_add_u32_e32 v0, s37, v0
	s_movk_i32 s0, 0x2200
	v_bfe_u32 v66, v70, 4, 2
	v_and_b32_e32 v68, 32, v70
	v_and_b32_e32 v69, 24, v69
	v_mul_lo_u32 v0, v0, s0
	v_or3_b32 v188, v68, v69, v0
	v_or_b32_e32 v0, s5, v66
	v_lshlrev_b32_e32 v0, s41, v0
	v_add_u32_e32 v0, s37, v0
	v_bitop3_b32 v68, v66, v70, 15 bitop3:0x78
	v_mul_lo_u32 v0, v0, s0
	v_lshl_or_b32 v0, v68, 3, v0
	v_or_b32_e32 v68, 4, v66
	v_and_b32_e32 v67, 15, v70
	v_or_b32_e32 v68, s5, v68
	v_bitop3_b32 v66, v66, v67, 4 bitop3:0x36
	v_lshlrev_b32_e32 v67, s41, v68
	v_add_u32_e32 v67, s37, v67
	v_mul_lo_u32 v67, v67, s0
	s_mov_b32 s0, 0x220000
	s_cselect_b32 s42, s0, 0x440000
	s_lshl_b32 s0, s4, 11
	s_add_i32 s1, 0, 0x10000
	s_add_i32 s43, s1, s0
	v_lshl_add_u64 v[68:69], v[0:1], 1, s[16:17]
	s_mov_b32 m0, s43
	s_add_i32 s44, s0, 0
	v_lshl_or_b32 v190, v66, 3, v67
	global_load_lds_dwordx4 v[68:69], off
	v_lshl_add_u64 v[68:69], v[188:189], 1, s[18:19]
	s_mov_b32 m0, s44
	s_or_b32 s5, s0, 0x400
	global_load_lds_dwordx4 v[68:69], off
	v_lshl_add_u64 v[68:69], v[190:191], 1, s[16:17]
	s_add_i32 m0, s1, s5
	v_or_b32_e32 v66, 64, v188
	global_load_lds_dwordx4 v[68:69], off
	s_add_i32 m0, s44, 0x400
	v_mov_b32_e32 v67, v1
	s_cmp_gt_i32 s4, 3
	v_lshl_add_u64 v[68:69], v[66:67], 1, s[18:19]
	s_cselect_b64 s[20:21], -1, 0
	s_cmp_lt_i32 s4, 4
	global_load_lds_dwordx4 v[68:69], off
	s_cselect_b64 s[22:23], -1, 0
	v_add_u32_e32 v68, s42, v0
	v_mov_b32_e32 v69, v1
	s_add_i32 s1, 0, 0x14000
	v_lshl_add_u64 v[68:69], v[68:69], 1, s[16:17]
	s_add_i32 m0, s1, s0
	v_add_u32_e32 v66, s42, v66
	global_load_lds_dwordx4 v[68:69], off
	v_add_u32_e32 v68, s42, v188
	v_mov_b32_e32 v69, v1
	v_lshl_add_u64 v[68:69], v[68:69], 1, s[18:19]
	s_add_i32 m0, s44, 0x4000
	v_lshl_add_u64 v[66:67], v[66:67], 1, s[18:19]
	global_load_lds_dwordx4 v[68:69], off
	v_add_u32_e32 v68, s42, v190
	v_mov_b32_e32 v69, v1
	v_lshl_add_u64 v[68:69], v[68:69], 1, s[16:17]
	s_add_i32 m0, s1, s5
	v_readlane_b32 s0, v254, 1
	global_load_lds_dwordx4 v[68:69], off
	s_add_i32 m0, s44, 0x4400
	v_and_b32_e32 v69, 0x3fffffc0, v70
	global_load_lds_dwordx4 v[66:67], off
	v_and_b32_e32 v66, 63, v70
	v_lshlrev_b32_e32 v71, 4, v70
	v_and_b32_e32 v67, 31, v70
	v_bfe_u32 v68, v70, 5, 1
	v_lshl_add_u32 v189, v69, 2, s0
	v_lshlrev_b32_e32 v69, 3, v66
	v_and_b32_e32 v72, 0xc0, v71
	v_lshlrev_b32_e32 v70, 1, v70
	v_and_or_b32 v72, v69, 24, v72
	v_and_b32_e32 v70, 32, v70
	v_and_b32_e32 v69, 0x100, v69
	v_lshlrev_b32_e32 v199, 4, v68
	s_movk_i32 s0, 0x70
	v_or3_b32 v69, v72, v70, v69
	v_and_b32_e32 v70, 0x70, v71
	v_bitop3_b32 v216, v199, v71, s0 bitop3:0x78
	s_movk_i32 s0, 0x60
	s_and_b64 s[4:5], s[12:13], exec
	v_bitop3_b32 v219, v199, v70, s0 bitop3:0x36
	s_waitcnt vmcnt(4)
	v_cmp_gt_u32_e64 s[0:1], 32, v66
	s_movk_i32 s4, 0x1f8
	v_and_b32_e32 v66, s40, v223
	v_mov_b32_e32 v81, v1
	v_lshlrev_b32_e32 v191, 8, v67
	v_bitop3_b32 v217, v199, v70, 32 bitop3:0x36
	v_bitop3_b32 v218, v199, v70, 64 bitop3:0x36
	v_add_u32_e32 v220, 0, v69
	v_lshl_add_u32 v221, v67, 2, v189
	s_cselect_b32 s46, 0xfc, s4
	v_mul_i32_i24_e32 v222, -4, v68
	v_cmp_eq_u32_e64 s[4:5], 0, v66
	s_lshl_b32 s6, s38, 6
	v_mov_b32_e32 v66, v1
	v_mov_b32_e32 v67, v1
	v_mov_b32_e32 v68, v1
	v_mov_b32_e32 v69, v1
	v_mov_b32_e32 v70, v1
	v_mov_b32_e32 v71, v1
	v_mov_b32_e32 v72, v1
	v_mov_b32_e32 v73, v1
	v_mov_b32_e32 v74, v1
	v_mov_b32_e32 v75, v1
	v_mov_b32_e32 v76, v1
	v_mov_b32_e32 v77, v1
	v_mov_b32_e32 v78, v1
	v_mov_b32_e32 v79, v1
	v_mov_b64_e32 v[96:97], v[80:81]
	s_or_b32 s47, s6, 64
	s_lshl_b32 s48, s42, 1
	s_mov_b64 s[6:7], 0
	v_mov_b32_e32 v200, v0
	v_mov_b64_e32 v[94:95], v[78:79]
	v_mov_b64_e32 v[92:93], v[76:77]
	v_mov_b64_e32 v[90:91], v[74:75]
	v_mov_b64_e32 v[88:89], v[72:73]
	v_mov_b64_e32 v[86:87], v[70:71]
	v_mov_b64_e32 v[84:85], v[68:69]
	v_mov_b64_e32 v[82:83], v[66:67]
	s_waitcnt vmcnt(4) lgkmcnt(0)
	s_barrier
	s_branch .LBB0_1251
